# v64 + static priority: K-loop per-cluster s_setprio flips deleted, one static s_setprio 1 for waves 4-7 at GEMM phase entry
# speedup vs baseline: 1.0033x; 1.0033x over previous
; __device__ __forceinline__ void convert_WA(const Ctx& F, int l) { convert_weights<false>(F, l); }
; __global__ void __launch_bounds__(512, 2) fwd_kernel(Params prm) {
;     ...
;     for (int ph = lo; ph < hi; ++ph) {
;         if (ph > lo) { if (lo < 0) cg::this_grid().sync(); else xcd_barrier(xbar); }
;         int wv_ = wave0; asm volatile("" : "+s"(wv_));
;         int ln_; asm volatile("v_mbcnt_lo_u32_b32 %0, -1, 0\n\tv_mbcnt_hi_u32_b32 %0, -1, %0" : "=v"(ln_));
;         F.wave = wv_; F.lane = ln_; F.tid = wv_ * 64 + ln_;
;         size_t wz_ = 0; asm volatile("" : "+s"(wz_));
;         unsigned char* ws = prm.ws + wz_;
;         float* MOD = (float*)(ws + OFF_MOD);
;         float* ctxres = (float*)(ws + OFF_CTX);
;         bf16_t* GRb = (bf16_t*)(ws + OFF_GR); bf16_t* Qb = (bf16_t*)(ws + OFF_Q); bf16_t* KVb = (bf16_t*)(ws + OFF_KV); bf16_t* GLb = (bf16_t*)(ws + OFF_GL);
;         bf16_t* RX = (bf16_t*)(ws + OFF_X); bf16_t* RY = (bf16_t*)(ws + OFF_Y);
;         bf16_t* A2 = (bf16_t*)(ws + OFF_A2); bf16_t* Fb = (bf16_t*)(ws + OFF_F); bf16_t* Mx = (bf16_t*)(ws + OFF_MX);
;         if (ph == 0) {
;             if (F.bid == F.G - 1) { float* TAB = (float*)(ws + OFF_TAB);
;                 for (int i = F.tid; i < 64 * 32; i += 512) { const int pos = i >> 5, f = i & 31; float sn, cs; sincosf((float)pos * exp2f(-(float)f * (13.287712379549449f / 32.0f)), &sn, &cs); TAB[2 * i] = cs; TAB[2 * i + 1] = sn; } }
;             mod_phase(F); __syncthreads(); convert_WA(F, 0); continue; }
;         if (ph == 1) { norm_phase<false, true>(F, MT, prm.in[0], prm.in[2], nullptr, nullptr, nullptr, nullptr, 0, nullptr, nullptr, prm.in[6], MOD, 1024, 0, RY); continue; }
;         const int l = (ph - 2) / 9, sp = (ph - 2) % 9;
.Lnrm_ret:
	v_readlane_b32 s73, v252, 7
	s_setprio 0
	s_mov_b32 s0, 0x6cb64
	s_bitcmp1_b32 s0, s72
	s_cbranch_scc0 .Lsp_done
	s_nop 3
	s_cmp_ge_u32 s73, 4
	s_cbranch_scc0 .Lsp_done
	s_setprio 1
.Lsp_done:
	s_mov_b64 s[40:41], 0
	v_mbcnt_lo_u32_b32 v166, -1, 0
	v_mbcnt_hi_u32_b32 v166, -1, v166
	s_add_u32 s2, s66, s40
	s_addc_u32 s97, s67, s41
	s_add_u32 s0, s2, 0x1600000
	s_addc_u32 s1, s97, 0
	s_mov_b64 s[14:15], -1
	s_mov_b64 s[4:5], 0
	s_cmp_lt_i32 s72, 1
	s_mov_b64 s[12:13], 0
	s_cbranch_scc1 .LBB0_86
	s_cmp_eq_u32 s72, 1
	s_mov_b64 s[12:13], -1
	s_cbranch_scc0 .LBB0_90
	s_branch .LBB0_89

.LBB0_184:
	s_add_i32 s90, s58, 2
	s_add_u32 s56, s54, 0x100
	s_addc_u32 s57, s55, 0
	s_add_i32 s91, 0, 0x10000
	s_cmp_eq_u32 s46, s58
	s_cselect_b32 s61, s18, s57
	s_cselect_b32 s60, s19, s56
	v_add_u32_e32 v140, s91, v143
	s_cselect_b32 s59, s22, s89
	s_cselect_b32 s58, s23, s47
	s_add_i32 vcc_lo, 0, 0x14000
	ds_read_b128 v[146:149], v140
	ds_read_b128 v[150:153], v140 offset:1024
	ds_read_b128 v[154:157], v140 offset:2048
	ds_read_b128 v[158:161], v140 offset:3072
	v_add_u32_e32 v140, vcc_lo, v143
	ds_read_b128 v[162:165], v140
	ds_read_b128 v[176:179], v140 offset:1024
	ds_read_b128 v[180:183], v140 offset:2048
	ds_read_b128 v[184:187], v140 offset:3072
	v_lshl_add_u64 v[140:141], s[54:55], 0, v[136:137]
	s_add_i32 m0, s39, 0xc000
	ds_read_b128 v[188:191], v144
	ds_read_b128 v[192:195], v144 offset:1024
	ds_read_b128 v[196:199], v144 offset:2048
	ds_read_b128 v[200:203], v144 offset:3072
	ds_read_b128 v[204:207], v144 offset:4096
	ds_read_b128 v[208:211], v144 offset:5120
	ds_read_b128 v[212:215], v144 offset:6144
	ds_read_b128 v[220:223], v144 offset:7168
	global_load_lds_dwordx4 v[140:141], off
	v_lshl_add_u64 v[140:141], s[54:55], 0, v[138:139]
	s_add_i32 m0, s39, 0xe000
	s_nop 0
	global_load_lds_dwordx4 v[140:141], off
	s_waitcnt vmcnt(8)
	s_waitcnt lgkmcnt(0)
	s_barrier
	s_waitcnt lgkmcnt(0)
	v_mfma_f32_16x16x32_bf16 v[126:129], v[146:149], v[188:191], v[126:129]
	v_mfma_f32_16x16x32_bf16 v[122:125], v[154:157], v[188:191], v[122:125]
	v_mfma_f32_16x16x32_bf16 v[118:121], v[146:149], v[196:199], v[118:121]
	v_mfma_f32_16x16x32_bf16 v[110:113], v[154:157], v[196:199], v[110:113]
	v_mfma_f32_16x16x32_bf16 v[102:105], v[146:149], v[204:207], v[102:105]
	v_mfma_f32_16x16x32_bf16 v[94:97], v[154:157], v[204:207], v[94:97]
	v_mfma_f32_16x16x32_bf16 v[86:89], v[146:149], v[212:215], v[86:89]
	v_mfma_f32_16x16x32_bf16 v[78:81], v[154:157], v[212:215], v[78:81]
	v_mfma_f32_16x16x32_bf16 v[126:129], v[150:153], v[192:195], v[126:129]
	v_mfma_f32_16x16x32_bf16 v[122:125], v[158:161], v[192:195], v[122:125]
	v_mfma_f32_16x16x32_bf16 v[118:121], v[150:153], v[200:203], v[118:121]
	v_mfma_f32_16x16x32_bf16 v[110:113], v[158:161], v[200:203], v[110:113]
	v_mfma_f32_16x16x32_bf16 v[102:105], v[150:153], v[208:211], v[102:105]
	v_mfma_f32_16x16x32_bf16 v[94:97], v[158:161], v[208:211], v[94:97]
	v_mfma_f32_16x16x32_bf16 v[86:89], v[150:153], v[220:223], v[86:89]
	v_mfma_f32_16x16x32_bf16 v[78:81], v[158:161], v[220:223], v[78:81]
	v_mfma_f32_16x16x32_bf16 v[114:117], v[162:165], v[188:191], v[114:117]
	v_mfma_f32_16x16x32_bf16 v[106:109], v[180:183], v[188:191], v[106:109]
	v_mfma_f32_16x16x32_bf16 v[98:101], v[162:165], v[196:199], v[98:101]
	v_mfma_f32_16x16x32_bf16 v[90:93], v[180:183], v[196:199], v[90:93]
	v_mfma_f32_16x16x32_bf16 v[82:85], v[162:165], v[204:207], v[82:85]
	v_mfma_f32_16x16x32_bf16 v[74:77], v[180:183], v[204:207], v[74:77]
	v_mfma_f32_16x16x32_bf16 v[70:73], v[162:165], v[212:215], v[70:73]
	v_mfma_f32_16x16x32_bf16 v[66:69], v[180:183], v[212:215], v[66:69]
	v_mfma_f32_16x16x32_bf16 v[114:117], v[176:179], v[192:195], v[114:117]
	v_mfma_f32_16x16x32_bf16 v[106:109], v[184:187], v[192:195], v[106:109]
	v_mfma_f32_16x16x32_bf16 v[98:101], v[176:179], v[200:203], v[98:101]
	v_mfma_f32_16x16x32_bf16 v[90:93], v[184:187], v[200:203], v[90:93]
	v_mfma_f32_16x16x32_bf16 v[82:85], v[176:179], v[208:211], v[82:85]
	v_mfma_f32_16x16x32_bf16 v[74:77], v[184:187], v[208:211], v[74:77]
	v_mfma_f32_16x16x32_bf16 v[70:73], v[176:179], v[220:223], v[70:73]
	v_mfma_f32_16x16x32_bf16 v[66:69], v[184:187], v[220:223], v[66:69]
	s_barrier
	s_add_i32 s54, s91, s38
	v_lshl_add_u64 v[140:141], s[58:59], 0, v[32:33]
	s_mov_b32 m0, s54
	ds_read_b128 v[188:191], v144 offset:16384
	ds_read_b128 v[192:195], v144 offset:17408
	ds_read_b128 v[196:199], v144 offset:18432
	ds_read_b128 v[200:203], v144 offset:19456
	ds_read_b128 v[204:207], v144 offset:20480
	ds_read_b128 v[208:211], v144 offset:21504
	ds_read_b128 v[212:215], v144 offset:22528
	ds_read_b128 v[220:223], v144 offset:23552
	global_load_lds_dwordx4 v[140:141], off
	s_add_i32 m0, s54, 0x2000
	s_add_u32 s54, s58, 0xb0000
	v_lshl_add_u64 v[224:225], s[58:59], 0, v[134:135]
	s_addc_u32 s55, s59, 0
	s_add_i32 s91, vcc_lo, s38
	global_load_lds_dwordx4 v[224:225], off
	v_lshl_add_u64 v[226:227], s[54:55], 0, v[32:33]
	s_mov_b32 m0, s91
	v_lshl_add_u64 v[228:229], s[60:61], 0, v[132:133]
	global_load_lds_dwordx4 v[226:227], off
	v_lshl_add_u64 v[226:227], s[54:55], 0, v[134:135]
	s_add_i32 m0, s91, 0x2000
	s_nop 0
	global_load_lds_dwordx4 v[226:227], off
	v_lshl_add_u64 v[226:227], s[60:61], 0, v[130:131]
	s_mov_b32 m0, s39
	s_nop 0
	global_load_lds_dwordx4 v[226:227], off
	s_mov_b32 m0, s62
	s_nop 0
	global_load_lds_dwordx4 v[228:229], off
	s_waitcnt vmcnt(8)
	s_waitcnt lgkmcnt(0)
	s_barrier
	s_waitcnt lgkmcnt(0)
	v_mfma_f32_16x16x32_bf16 v[62:65], v[146:149], v[188:191], v[62:65]
	v_mfma_f32_16x16x32_bf16 v[58:61], v[154:157], v[188:191], v[58:61]
	v_mfma_f32_16x16x32_bf16 v[54:57], v[146:149], v[196:199], v[54:57]
	v_mfma_f32_16x16x32_bf16 v[46:49], v[154:157], v[196:199], v[46:49]
	v_mfma_f32_16x16x32_bf16 v[38:41], v[146:149], v[204:207], v[38:41]
	v_mfma_f32_16x16x32_bf16 v[28:31], v[154:157], v[204:207], v[28:31]
	v_mfma_f32_16x16x32_bf16 v[20:23], v[146:149], v[212:215], v[20:23]
	v_mfma_f32_16x16x32_bf16 v[12:15], v[154:157], v[212:215], v[12:15]
	v_mfma_f32_16x16x32_bf16 v[62:65], v[150:153], v[192:195], v[62:65]
	v_mfma_f32_16x16x32_bf16 v[58:61], v[158:161], v[192:195], v[58:61]
	v_mfma_f32_16x16x32_bf16 v[54:57], v[150:153], v[200:203], v[54:57]
	v_mfma_f32_16x16x32_bf16 v[46:49], v[158:161], v[200:203], v[46:49]
	v_mfma_f32_16x16x32_bf16 v[38:41], v[150:153], v[208:211], v[38:41]
	v_mfma_f32_16x16x32_bf16 v[28:31], v[158:161], v[208:211], v[28:31]
	v_mfma_f32_16x16x32_bf16 v[20:23], v[150:153], v[220:223], v[20:23]
	v_mfma_f32_16x16x32_bf16 v[12:15], v[158:161], v[220:223], v[12:15]
	v_mfma_f32_16x16x32_bf16 v[50:53], v[162:165], v[188:191], v[50:53]
	v_mfma_f32_16x16x32_bf16 v[42:45], v[180:183], v[188:191], v[42:45]
	v_mfma_f32_16x16x32_bf16 v[34:37], v[162:165], v[196:199], v[34:37]
	v_mfma_f32_16x16x32_bf16 v[24:27], v[180:183], v[196:199], v[24:27]
	v_mfma_f32_16x16x32_bf16 v[16:19], v[162:165], v[204:207], v[16:19]
	v_mfma_f32_16x16x32_bf16 v[8:11], v[180:183], v[204:207], v[8:11]
	v_mfma_f32_16x16x32_bf16 v[4:7], v[162:165], v[212:215], v[4:7]
	v_mfma_f32_16x16x32_bf16 v[0:3], v[180:183], v[212:215], v[0:3]
	v_mfma_f32_16x16x32_bf16 v[50:53], v[176:179], v[192:195], v[50:53]
	v_mfma_f32_16x16x32_bf16 v[42:45], v[184:187], v[192:195], v[42:45]
	v_mfma_f32_16x16x32_bf16 v[34:37], v[176:179], v[200:203], v[34:37]
	v_mfma_f32_16x16x32_bf16 v[24:27], v[184:187], v[200:203], v[24:27]
	v_mfma_f32_16x16x32_bf16 v[16:19], v[176:179], v[208:211], v[16:19]
	v_mfma_f32_16x16x32_bf16 v[8:11], v[184:187], v[208:211], v[8:11]
	v_mfma_f32_16x16x32_bf16 v[4:7], v[176:179], v[220:223], v[4:7]
	v_mfma_f32_16x16x32_bf16 v[0:3], v[184:187], v[220:223], v[0:3]
	s_barrier
	s_add_i32 s91, 0, 0x18000
	v_add_u32_e32 v145, s91, v143
	s_add_i32 vcc_lo, 0, 0x1c000
	ds_read_b128 v[146:149], v145
	ds_read_b128 v[150:153], v145 offset:1024
	ds_read_b128 v[154:157], v145 offset:2048
	ds_read_b128 v[158:161], v145 offset:3072
	v_add_u32_e32 v145, vcc_lo, v143
	ds_read_b128 v[162:165], v145
	ds_read_b128 v[176:179], v145 offset:1024
	ds_read_b128 v[180:183], v145 offset:2048
	ds_read_b128 v[184:187], v145 offset:3072
	s_add_u32 s54, s60, 0xb0000
	s_addc_u32 s55, s61, 0
	s_mov_b32 m0, s63
	v_lshl_add_u64 v[230:231], s[54:55], 0, v[130:131]
	ds_read_b128 v[188:191], v144 offset:32768
	ds_read_b128 v[192:195], v144 offset:33792
	ds_read_b128 v[196:199], v144 offset:34816
	ds_read_b128 v[200:203], v144 offset:35840
	ds_read_b128 v[204:207], v144 offset:36864
	ds_read_b128 v[208:211], v144 offset:37888
	ds_read_b128 v[212:215], v144 offset:38912
	ds_read_b128 v[220:223], v144 offset:39936
	global_load_lds_dwordx4 v[230:231], off
	v_lshl_add_u64 v[230:231], s[54:55], 0, v[132:133]
	s_mov_b32 m0, s64
	s_nop 0
	global_load_lds_dwordx4 v[230:231], off
	s_waitcnt vmcnt(8)
	s_waitcnt lgkmcnt(0)
	s_barrier
	s_waitcnt lgkmcnt(0)
	v_mfma_f32_16x16x32_bf16 v[126:129], v[146:149], v[188:191], v[126:129]
	v_mfma_f32_16x16x32_bf16 v[122:125], v[154:157], v[188:191], v[122:125]
	v_mfma_f32_16x16x32_bf16 v[118:121], v[146:149], v[196:199], v[118:121]
	v_mfma_f32_16x16x32_bf16 v[110:113], v[154:157], v[196:199], v[110:113]
	v_mfma_f32_16x16x32_bf16 v[102:105], v[146:149], v[204:207], v[102:105]
	v_mfma_f32_16x16x32_bf16 v[94:97], v[154:157], v[204:207], v[94:97]
	v_mfma_f32_16x16x32_bf16 v[86:89], v[146:149], v[212:215], v[86:89]
	v_mfma_f32_16x16x32_bf16 v[78:81], v[154:157], v[212:215], v[78:81]
	v_mfma_f32_16x16x32_bf16 v[126:129], v[150:153], v[192:195], v[126:129]
	v_mfma_f32_16x16x32_bf16 v[122:125], v[158:161], v[192:195], v[122:125]
	v_mfma_f32_16x16x32_bf16 v[118:121], v[150:153], v[200:203], v[118:121]
	v_mfma_f32_16x16x32_bf16 v[110:113], v[158:161], v[200:203], v[110:113]
	v_mfma_f32_16x16x32_bf16 v[102:105], v[150:153], v[208:211], v[102:105]
	v_mfma_f32_16x16x32_bf16 v[94:97], v[158:161], v[208:211], v[94:97]
	v_mfma_f32_16x16x32_bf16 v[86:89], v[150:153], v[220:223], v[86:89]
	v_mfma_f32_16x16x32_bf16 v[78:81], v[158:161], v[220:223], v[78:81]
	v_mfma_f32_16x16x32_bf16 v[114:117], v[162:165], v[188:191], v[114:117]
	v_mfma_f32_16x16x32_bf16 v[106:109], v[180:183], v[188:191], v[106:109]
	v_mfma_f32_16x16x32_bf16 v[98:101], v[162:165], v[196:199], v[98:101]
	v_mfma_f32_16x16x32_bf16 v[90:93], v[180:183], v[196:199], v[90:93]
	v_mfma_f32_16x16x32_bf16 v[82:85], v[162:165], v[204:207], v[82:85]
	v_mfma_f32_16x16x32_bf16 v[74:77], v[180:183], v[204:207], v[74:77]
	v_mfma_f32_16x16x32_bf16 v[70:73], v[162:165], v[212:215], v[70:73]
	v_mfma_f32_16x16x32_bf16 v[66:69], v[180:183], v[212:215], v[66:69]
	v_mfma_f32_16x16x32_bf16 v[114:117], v[176:179], v[192:195], v[114:117]
	v_mfma_f32_16x16x32_bf16 v[106:109], v[184:187], v[192:195], v[106:109]
	v_mfma_f32_16x16x32_bf16 v[98:101], v[176:179], v[200:203], v[98:101]
	v_mfma_f32_16x16x32_bf16 v[90:93], v[184:187], v[200:203], v[90:93]
	v_mfma_f32_16x16x32_bf16 v[82:85], v[176:179], v[208:211], v[82:85]
	v_mfma_f32_16x16x32_bf16 v[74:77], v[184:187], v[208:211], v[74:77]
	v_mfma_f32_16x16x32_bf16 v[70:73], v[176:179], v[220:223], v[70:73]
	v_mfma_f32_16x16x32_bf16 v[66:69], v[184:187], v[220:223], v[66:69]
	s_barrier
	s_add_i32 s54, s91, s38
	v_lshl_add_u64 v[140:141], v[140:141], 0, s[28:29]
	s_mov_b32 m0, s54
	ds_read_b128 v[188:191], v144 offset:49152
	ds_read_b128 v[192:195], v144 offset:50176
	ds_read_b128 v[196:199], v144 offset:51200
	ds_read_b128 v[200:203], v144 offset:52224
	ds_read_b128 v[204:207], v144 offset:53248
	ds_read_b128 v[208:211], v144 offset:54272
	ds_read_b128 v[212:215], v144 offset:55296
	ds_read_b128 v[220:223], v144 offset:56320
	global_load_lds_dwordx4 v[140:141], off
	s_add_i32 m0, s54, 0x2000
	s_add_u32 s54, s58, 0xb0080
	v_lshl_add_u64 v[140:141], v[224:225], 0, s[28:29]
	s_addc_u32 s55, s59, 0
	s_add_i32 s58, vcc_lo, s38
	global_load_lds_dwordx4 v[140:141], off
	v_lshl_add_u64 v[140:141], s[54:55], 0, v[32:33]
	s_mov_b32 m0, s58
	s_nop 0
	global_load_lds_dwordx4 v[140:141], off
	v_lshl_add_u64 v[140:141], s[54:55], 0, v[134:135]
	s_add_i32 m0, s58, 0x2000
	s_nop 0
	global_load_lds_dwordx4 v[140:141], off
	v_lshl_add_u64 v[140:141], v[226:227], 0, s[28:29]
	s_mov_b32 m0, s67
	s_nop 0
	global_load_lds_dwordx4 v[140:141], off
	v_lshl_add_u64 v[140:141], v[228:229], 0, s[28:29]
	s_mov_b32 m0, s77
	s_nop 0
	global_load_lds_dwordx4 v[140:141], off
	s_waitcnt vmcnt(8)
	s_waitcnt lgkmcnt(0)
	s_barrier
	s_waitcnt lgkmcnt(0)
	v_mfma_f32_16x16x32_bf16 v[62:65], v[146:149], v[188:191], v[62:65]
	v_mfma_f32_16x16x32_bf16 v[58:61], v[154:157], v[188:191], v[58:61]
	v_mfma_f32_16x16x32_bf16 v[54:57], v[146:149], v[196:199], v[54:57]
	v_mfma_f32_16x16x32_bf16 v[46:49], v[154:157], v[196:199], v[46:49]
	v_mfma_f32_16x16x32_bf16 v[38:41], v[146:149], v[204:207], v[38:41]
	v_mfma_f32_16x16x32_bf16 v[28:31], v[154:157], v[204:207], v[28:31]
	v_mfma_f32_16x16x32_bf16 v[20:23], v[146:149], v[212:215], v[20:23]
	v_mfma_f32_16x16x32_bf16 v[12:15], v[154:157], v[212:215], v[12:15]
	v_mfma_f32_16x16x32_bf16 v[62:65], v[150:153], v[192:195], v[62:65]
	v_mfma_f32_16x16x32_bf16 v[58:61], v[158:161], v[192:195], v[58:61]
	v_mfma_f32_16x16x32_bf16 v[54:57], v[150:153], v[200:203], v[54:57]
	v_mfma_f32_16x16x32_bf16 v[46:49], v[158:161], v[200:203], v[46:49]
	v_mfma_f32_16x16x32_bf16 v[38:41], v[150:153], v[208:211], v[38:41]
	v_mfma_f32_16x16x32_bf16 v[28:31], v[158:161], v[208:211], v[28:31]
	v_mfma_f32_16x16x32_bf16 v[20:23], v[150:153], v[220:223], v[20:23]
	v_mfma_f32_16x16x32_bf16 v[12:15], v[158:161], v[220:223], v[12:15]
	v_mfma_f32_16x16x32_bf16 v[50:53], v[162:165], v[188:191], v[50:53]
	v_mfma_f32_16x16x32_bf16 v[42:45], v[180:183], v[188:191], v[42:45]
	v_mfma_f32_16x16x32_bf16 v[34:37], v[162:165], v[196:199], v[34:37]
	v_mfma_f32_16x16x32_bf16 v[24:27], v[180:183], v[196:199], v[24:27]
	v_mfma_f32_16x16x32_bf16 v[16:19], v[162:165], v[204:207], v[16:19]
	v_mfma_f32_16x16x32_bf16 v[8:11], v[180:183], v[204:207], v[8:11]
	v_mfma_f32_16x16x32_bf16 v[4:7], v[162:165], v[212:215], v[4:7]
	v_mfma_f32_16x16x32_bf16 v[0:3], v[180:183], v[212:215], v[0:3]
	v_mfma_f32_16x16x32_bf16 v[50:53], v[176:179], v[192:195], v[50:53]
	v_mfma_f32_16x16x32_bf16 v[42:45], v[184:187], v[192:195], v[42:45]
	v_mfma_f32_16x16x32_bf16 v[34:37], v[176:179], v[200:203], v[34:37]
	v_mfma_f32_16x16x32_bf16 v[24:27], v[184:187], v[200:203], v[24:27]
	v_mfma_f32_16x16x32_bf16 v[16:19], v[176:179], v[208:211], v[16:19]
	v_mfma_f32_16x16x32_bf16 v[8:11], v[184:187], v[208:211], v[8:11]
	v_mfma_f32_16x16x32_bf16 v[4:7], v[176:179], v[220:223], v[4:7]
	v_mfma_f32_16x16x32_bf16 v[0:3], v[184:187], v[220:223], v[0:3]
	s_barrier
	s_add_u32 s47, s47, 0x100
	s_addc_u32 s89, s89, 0
	s_cmp_ge_i32 s90, s84
	s_mov_b64 s[54:55], s[56:57]
	s_mov_b32 s58, s90
	s_cbranch_scc0 .LBB0_184
	s_and_b64 vcc, exec, s[26:27]
	s_cbranch_vccz .LBB0_187
	s_barrier

.LBB0_202:
	s_add_u32 s51, s62, 0xfffc0080
	s_addc_u32 s66, s63, -1
	s_add_i32 s79, 0, 0x10000
	s_cmp_eq_u32 s27, 12
	s_cselect_b32 vcc_hi, s59, s66
	s_cselect_b32 vcc_lo, s58, s51
	v_add_u32_e32 v140, s79, v143
	s_cselect_b32 s67, s61, s19
	s_cselect_b32 s66, s60, s18
	s_add_i32 s51, 0, 0x14000
	ds_read_b128 v[146:149], v140
	ds_read_b128 v[150:153], v140 offset:1024
	ds_read_b128 v[154:157], v140 offset:2048
	ds_read_b128 v[158:161], v140 offset:3072
	v_add_u32_e32 v140, s51, v143
	ds_read_b128 v[162:165], v140
	ds_read_b128 v[176:179], v140 offset:1024
	ds_read_b128 v[180:183], v140 offset:2048
	ds_read_b128 v[184:187], v140 offset:3072
	v_lshl_add_u64 v[140:141], s[62:63], 0, v[136:137]
	s_add_i32 m0, s33, 0xc000
	ds_read_b128 v[188:191], v144
	ds_read_b128 v[192:195], v144 offset:1024
	ds_read_b128 v[196:199], v144 offset:2048
	ds_read_b128 v[200:203], v144 offset:3072
	ds_read_b128 v[204:207], v144 offset:4096
	ds_read_b128 v[208:211], v144 offset:5120
	ds_read_b128 v[212:215], v144 offset:6144
	ds_read_b128 v[220:223], v144 offset:7168
	global_load_lds_dwordx4 v[140:141], off
	v_lshl_add_u64 v[140:141], s[62:63], 0, v[138:139]
	s_add_i32 m0, s33, 0xe000
	s_nop 0
	global_load_lds_dwordx4 v[140:141], off
	s_waitcnt vmcnt(8)
	s_waitcnt lgkmcnt(0)
	s_barrier
	s_waitcnt lgkmcnt(0)
	v_mfma_f32_16x16x32_bf16 v[126:129], v[146:149], v[188:191], v[126:129]
	v_mfma_f32_16x16x32_bf16 v[118:121], v[154:157], v[188:191], v[118:121]
	v_mfma_f32_16x16x32_bf16 v[110:113], v[146:149], v[196:199], v[110:113]
	v_mfma_f32_16x16x32_bf16 v[102:105], v[154:157], v[196:199], v[102:105]
	v_mfma_f32_16x16x32_bf16 v[94:97], v[146:149], v[204:207], v[94:97]
	v_mfma_f32_16x16x32_bf16 v[86:89], v[154:157], v[204:207], v[86:89]
	v_mfma_f32_16x16x32_bf16 v[78:81], v[146:149], v[212:215], v[78:81]
	v_mfma_f32_16x16x32_bf16 v[70:73], v[154:157], v[212:215], v[70:73]
	v_mfma_f32_16x16x32_bf16 v[126:129], v[150:153], v[192:195], v[126:129]
	v_mfma_f32_16x16x32_bf16 v[118:121], v[158:161], v[192:195], v[118:121]
	v_mfma_f32_16x16x32_bf16 v[110:113], v[150:153], v[200:203], v[110:113]
	v_mfma_f32_16x16x32_bf16 v[102:105], v[158:161], v[200:203], v[102:105]
	v_mfma_f32_16x16x32_bf16 v[94:97], v[150:153], v[208:211], v[94:97]
	v_mfma_f32_16x16x32_bf16 v[86:89], v[158:161], v[208:211], v[86:89]
	v_mfma_f32_16x16x32_bf16 v[78:81], v[150:153], v[220:223], v[78:81]
	v_mfma_f32_16x16x32_bf16 v[70:73], v[158:161], v[220:223], v[70:73]
	v_mfma_f32_16x16x32_bf16 v[122:125], v[162:165], v[188:191], v[122:125]
	v_mfma_f32_16x16x32_bf16 v[114:117], v[180:183], v[188:191], v[114:117]
	v_mfma_f32_16x16x32_bf16 v[106:109], v[162:165], v[196:199], v[106:109]
	v_mfma_f32_16x16x32_bf16 v[98:101], v[180:183], v[196:199], v[98:101]
	v_mfma_f32_16x16x32_bf16 v[90:93], v[162:165], v[204:207], v[90:93]
	v_mfma_f32_16x16x32_bf16 v[82:85], v[180:183], v[204:207], v[82:85]
	v_mfma_f32_16x16x32_bf16 v[74:77], v[162:165], v[212:215], v[74:77]
	v_mfma_f32_16x16x32_bf16 v[66:69], v[180:183], v[212:215], v[66:69]
	v_mfma_f32_16x16x32_bf16 v[122:125], v[176:179], v[192:195], v[122:125]
	v_mfma_f32_16x16x32_bf16 v[114:117], v[184:187], v[192:195], v[114:117]
	v_mfma_f32_16x16x32_bf16 v[106:109], v[176:179], v[200:203], v[106:109]
	v_mfma_f32_16x16x32_bf16 v[98:101], v[184:187], v[200:203], v[98:101]
	v_mfma_f32_16x16x32_bf16 v[90:93], v[176:179], v[208:211], v[90:93]
	v_mfma_f32_16x16x32_bf16 v[82:85], v[184:187], v[208:211], v[82:85]
	v_mfma_f32_16x16x32_bf16 v[74:77], v[176:179], v[220:223], v[74:77]
	v_mfma_f32_16x16x32_bf16 v[66:69], v[184:187], v[220:223], v[66:69]
	s_barrier
	s_add_i32 s79, s79, s1
	v_lshl_add_u64 v[140:141], s[66:67], 0, v[32:33]
	s_mov_b32 m0, s79
	ds_read_b128 v[188:191], v144 offset:16384
	ds_read_b128 v[192:195], v144 offset:17408
	ds_read_b128 v[196:199], v144 offset:18432
	ds_read_b128 v[200:203], v144 offset:19456
	ds_read_b128 v[204:207], v144 offset:20480
	ds_read_b128 v[208:211], v144 offset:21504
	ds_read_b128 v[212:215], v144 offset:22528
	ds_read_b128 v[220:223], v144 offset:23552
	global_load_lds_dwordx4 v[140:141], off
	s_add_i32 m0, s79, 0x2000
	s_add_u32 s84, s66, 0x40000
	v_lshl_add_u64 v[224:225], s[66:67], 0, v[130:131]
	s_addc_u32 s85, s67, 0
	s_add_i32 s51, s51, s1
	global_load_lds_dwordx4 v[224:225], off
	v_lshl_add_u64 v[226:227], s[84:85], 0, v[32:33]
	s_mov_b32 m0, s51
	v_lshl_add_u64 v[228:229], vcc, 0, v[132:133]
	global_load_lds_dwordx4 v[226:227], off
	v_lshl_add_u64 v[226:227], s[84:85], 0, v[130:131]
	s_add_i32 m0, s51, 0x2000
	s_nop 0
	global_load_lds_dwordx4 v[226:227], off
	v_lshl_add_u64 v[226:227], vcc, 0, v[134:135]
	s_mov_b32 m0, s33
	s_nop 0
	global_load_lds_dwordx4 v[226:227], off
	s_mov_b32 m0, s38
	s_nop 0
	global_load_lds_dwordx4 v[228:229], off
	s_waitcnt vmcnt(8)
	s_waitcnt lgkmcnt(0)
	s_barrier
	s_waitcnt lgkmcnt(0)
	v_mfma_f32_16x16x32_bf16 v[62:65], v[146:149], v[188:191], v[62:65]
	v_mfma_f32_16x16x32_bf16 v[54:57], v[154:157], v[188:191], v[54:57]
	v_mfma_f32_16x16x32_bf16 v[46:49], v[146:149], v[196:199], v[46:49]
	v_mfma_f32_16x16x32_bf16 v[38:41], v[154:157], v[196:199], v[38:41]
	v_mfma_f32_16x16x32_bf16 v[28:31], v[146:149], v[204:207], v[28:31]
	v_mfma_f32_16x16x32_bf16 v[20:23], v[154:157], v[204:207], v[20:23]
	v_mfma_f32_16x16x32_bf16 v[12:15], v[146:149], v[212:215], v[12:15]
	v_mfma_f32_16x16x32_bf16 v[4:7], v[154:157], v[212:215], v[4:7]
	v_mfma_f32_16x16x32_bf16 v[62:65], v[150:153], v[192:195], v[62:65]
	v_mfma_f32_16x16x32_bf16 v[54:57], v[158:161], v[192:195], v[54:57]
	v_mfma_f32_16x16x32_bf16 v[46:49], v[150:153], v[200:203], v[46:49]
	v_mfma_f32_16x16x32_bf16 v[38:41], v[158:161], v[200:203], v[38:41]
	v_mfma_f32_16x16x32_bf16 v[28:31], v[150:153], v[208:211], v[28:31]
	v_mfma_f32_16x16x32_bf16 v[20:23], v[158:161], v[208:211], v[20:23]
	v_mfma_f32_16x16x32_bf16 v[12:15], v[150:153], v[220:223], v[12:15]
	v_mfma_f32_16x16x32_bf16 v[4:7], v[158:161], v[220:223], v[4:7]
	v_mfma_f32_16x16x32_bf16 v[58:61], v[162:165], v[188:191], v[58:61]
	v_mfma_f32_16x16x32_bf16 v[50:53], v[180:183], v[188:191], v[50:53]
	v_mfma_f32_16x16x32_bf16 v[42:45], v[162:165], v[196:199], v[42:45]
	v_mfma_f32_16x16x32_bf16 v[34:37], v[180:183], v[196:199], v[34:37]
	v_mfma_f32_16x16x32_bf16 v[24:27], v[162:165], v[204:207], v[24:27]
	v_mfma_f32_16x16x32_bf16 v[16:19], v[180:183], v[204:207], v[16:19]
	v_mfma_f32_16x16x32_bf16 v[8:11], v[162:165], v[212:215], v[8:11]
	v_mfma_f32_16x16x32_bf16 v[0:3], v[180:183], v[212:215], v[0:3]
	v_mfma_f32_16x16x32_bf16 v[58:61], v[176:179], v[192:195], v[58:61]
	v_mfma_f32_16x16x32_bf16 v[50:53], v[184:187], v[192:195], v[50:53]
	v_mfma_f32_16x16x32_bf16 v[42:45], v[176:179], v[200:203], v[42:45]
	v_mfma_f32_16x16x32_bf16 v[34:37], v[184:187], v[200:203], v[34:37]
	v_mfma_f32_16x16x32_bf16 v[24:27], v[176:179], v[208:211], v[24:27]
	v_mfma_f32_16x16x32_bf16 v[16:19], v[184:187], v[208:211], v[16:19]
	v_mfma_f32_16x16x32_bf16 v[8:11], v[176:179], v[220:223], v[8:11]
	v_mfma_f32_16x16x32_bf16 v[0:3], v[184:187], v[220:223], v[0:3]
	s_barrier
	s_add_i32 s51, 0, 0x18000
	v_add_u32_e32 v145, s51, v143
	s_add_i32 s79, 0, 0x1c000
	ds_read_b128 v[146:149], v145
	ds_read_b128 v[150:153], v145 offset:1024
	ds_read_b128 v[154:157], v145 offset:2048
	ds_read_b128 v[158:161], v145 offset:3072
	v_add_u32_e32 v145, s79, v143
	ds_read_b128 v[162:165], v145
	ds_read_b128 v[176:179], v145 offset:1024
	ds_read_b128 v[180:183], v145 offset:2048
	ds_read_b128 v[184:187], v145 offset:3072
	s_add_u32 s84, vcc_lo, 0x40000
	s_addc_u32 s85, vcc_hi, 0
	s_mov_b32 m0, s39
	v_lshl_add_u64 v[230:231], s[84:85], 0, v[134:135]
	ds_read_b128 v[188:191], v144 offset:32768
	ds_read_b128 v[192:195], v144 offset:33792
	ds_read_b128 v[196:199], v144 offset:34816
	ds_read_b128 v[200:203], v144 offset:35840
	ds_read_b128 v[204:207], v144 offset:36864
	ds_read_b128 v[208:211], v144 offset:37888
	ds_read_b128 v[212:215], v144 offset:38912
	ds_read_b128 v[220:223], v144 offset:39936
	global_load_lds_dwordx4 v[230:231], off
	v_lshl_add_u64 v[230:231], s[84:85], 0, v[132:133]
	s_mov_b32 m0, s46
	s_nop 0
	global_load_lds_dwordx4 v[230:231], off
	s_waitcnt vmcnt(8)
	s_waitcnt lgkmcnt(0)
	s_barrier
	s_waitcnt lgkmcnt(0)
	v_mfma_f32_16x16x32_bf16 v[126:129], v[146:149], v[188:191], v[126:129]
	v_mfma_f32_16x16x32_bf16 v[118:121], v[154:157], v[188:191], v[118:121]
	v_mfma_f32_16x16x32_bf16 v[110:113], v[146:149], v[196:199], v[110:113]
	v_mfma_f32_16x16x32_bf16 v[102:105], v[154:157], v[196:199], v[102:105]
	v_mfma_f32_16x16x32_bf16 v[94:97], v[146:149], v[204:207], v[94:97]
	v_mfma_f32_16x16x32_bf16 v[86:89], v[154:157], v[204:207], v[86:89]
	v_mfma_f32_16x16x32_bf16 v[78:81], v[146:149], v[212:215], v[78:81]
	v_mfma_f32_16x16x32_bf16 v[70:73], v[154:157], v[212:215], v[70:73]
	v_mfma_f32_16x16x32_bf16 v[126:129], v[150:153], v[192:195], v[126:129]
	v_mfma_f32_16x16x32_bf16 v[118:121], v[158:161], v[192:195], v[118:121]
	v_mfma_f32_16x16x32_bf16 v[110:113], v[150:153], v[200:203], v[110:113]
	v_mfma_f32_16x16x32_bf16 v[102:105], v[158:161], v[200:203], v[102:105]
	v_mfma_f32_16x16x32_bf16 v[94:97], v[150:153], v[208:211], v[94:97]
	v_mfma_f32_16x16x32_bf16 v[86:89], v[158:161], v[208:211], v[86:89]
	v_mfma_f32_16x16x32_bf16 v[78:81], v[150:153], v[220:223], v[78:81]
	v_mfma_f32_16x16x32_bf16 v[70:73], v[158:161], v[220:223], v[70:73]
	v_mfma_f32_16x16x32_bf16 v[122:125], v[162:165], v[188:191], v[122:125]
	v_mfma_f32_16x16x32_bf16 v[114:117], v[180:183], v[188:191], v[114:117]
	v_mfma_f32_16x16x32_bf16 v[106:109], v[162:165], v[196:199], v[106:109]
	v_mfma_f32_16x16x32_bf16 v[98:101], v[180:183], v[196:199], v[98:101]
	v_mfma_f32_16x16x32_bf16 v[90:93], v[162:165], v[204:207], v[90:93]
	v_mfma_f32_16x16x32_bf16 v[82:85], v[180:183], v[204:207], v[82:85]
	v_mfma_f32_16x16x32_bf16 v[74:77], v[162:165], v[212:215], v[74:77]
	v_mfma_f32_16x16x32_bf16 v[66:69], v[180:183], v[212:215], v[66:69]
	v_mfma_f32_16x16x32_bf16 v[122:125], v[176:179], v[192:195], v[122:125]
	v_mfma_f32_16x16x32_bf16 v[114:117], v[184:187], v[192:195], v[114:117]
	v_mfma_f32_16x16x32_bf16 v[106:109], v[176:179], v[200:203], v[106:109]
	v_mfma_f32_16x16x32_bf16 v[98:101], v[184:187], v[200:203], v[98:101]
	v_mfma_f32_16x16x32_bf16 v[90:93], v[176:179], v[208:211], v[90:93]
	v_mfma_f32_16x16x32_bf16 v[82:85], v[184:187], v[208:211], v[82:85]
	v_mfma_f32_16x16x32_bf16 v[74:77], v[176:179], v[220:223], v[74:77]
	v_mfma_f32_16x16x32_bf16 v[66:69], v[184:187], v[220:223], v[66:69]
	s_barrier
	s_add_i32 s51, s51, s1
	v_lshl_add_u64 v[140:141], v[140:141], 0, s[28:29]
	s_mov_b32 m0, s51
	ds_read_b128 v[188:191], v144 offset:49152
	ds_read_b128 v[192:195], v144 offset:50176
	ds_read_b128 v[196:199], v144 offset:51200
	ds_read_b128 v[200:203], v144 offset:52224
	ds_read_b128 v[204:207], v144 offset:53248
	ds_read_b128 v[208:211], v144 offset:54272
	ds_read_b128 v[212:215], v144 offset:55296
	ds_read_b128 v[220:223], v144 offset:56320
	global_load_lds_dwordx4 v[140:141], off
	s_add_i32 m0, s51, 0x2000
	s_add_u32 s66, s66, 0x40080
	v_lshl_add_u64 v[140:141], v[224:225], 0, s[28:29]
	s_addc_u32 s67, s67, 0
	s_add_i32 s51, s79, s1
	global_load_lds_dwordx4 v[140:141], off
	v_lshl_add_u64 v[140:141], s[66:67], 0, v[32:33]
	s_mov_b32 m0, s51
	s_nop 0
	global_load_lds_dwordx4 v[140:141], off
	v_lshl_add_u64 v[140:141], s[66:67], 0, v[130:131]
	s_add_i32 m0, s51, 0x2000
	s_nop 0
	global_load_lds_dwordx4 v[140:141], off
	v_lshl_add_u64 v[140:141], v[226:227], 0, s[28:29]
	s_mov_b32 m0, s64
	s_nop 0
	global_load_lds_dwordx4 v[140:141], off
	v_lshl_add_u64 v[140:141], v[228:229], 0, s[28:29]
	s_mov_b32 m0, s65
	s_nop 0
	global_load_lds_dwordx4 v[140:141], off
	s_waitcnt vmcnt(8)
	s_waitcnt lgkmcnt(0)
	s_barrier
	s_waitcnt lgkmcnt(0)
	v_mfma_f32_16x16x32_bf16 v[62:65], v[146:149], v[188:191], v[62:65]
	v_mfma_f32_16x16x32_bf16 v[54:57], v[154:157], v[188:191], v[54:57]
	v_mfma_f32_16x16x32_bf16 v[46:49], v[146:149], v[196:199], v[46:49]
	v_mfma_f32_16x16x32_bf16 v[38:41], v[154:157], v[196:199], v[38:41]
	v_mfma_f32_16x16x32_bf16 v[28:31], v[146:149], v[204:207], v[28:31]
	v_mfma_f32_16x16x32_bf16 v[20:23], v[154:157], v[204:207], v[20:23]
	v_mfma_f32_16x16x32_bf16 v[12:15], v[146:149], v[212:215], v[12:15]
	v_mfma_f32_16x16x32_bf16 v[4:7], v[154:157], v[212:215], v[4:7]
	v_mfma_f32_16x16x32_bf16 v[62:65], v[150:153], v[192:195], v[62:65]
	v_mfma_f32_16x16x32_bf16 v[54:57], v[158:161], v[192:195], v[54:57]
	v_mfma_f32_16x16x32_bf16 v[46:49], v[150:153], v[200:203], v[46:49]
	v_mfma_f32_16x16x32_bf16 v[38:41], v[158:161], v[200:203], v[38:41]
	v_mfma_f32_16x16x32_bf16 v[28:31], v[150:153], v[208:211], v[28:31]
	v_mfma_f32_16x16x32_bf16 v[20:23], v[158:161], v[208:211], v[20:23]
	v_mfma_f32_16x16x32_bf16 v[12:15], v[150:153], v[220:223], v[12:15]
	v_mfma_f32_16x16x32_bf16 v[4:7], v[158:161], v[220:223], v[4:7]
	v_mfma_f32_16x16x32_bf16 v[58:61], v[162:165], v[188:191], v[58:61]
	v_mfma_f32_16x16x32_bf16 v[50:53], v[180:183], v[188:191], v[50:53]
	v_mfma_f32_16x16x32_bf16 v[42:45], v[162:165], v[196:199], v[42:45]
	v_mfma_f32_16x16x32_bf16 v[34:37], v[180:183], v[196:199], v[34:37]
	v_mfma_f32_16x16x32_bf16 v[24:27], v[162:165], v[204:207], v[24:27]
	v_mfma_f32_16x16x32_bf16 v[16:19], v[180:183], v[204:207], v[16:19]
	v_mfma_f32_16x16x32_bf16 v[8:11], v[162:165], v[212:215], v[8:11]
	v_mfma_f32_16x16x32_bf16 v[0:3], v[180:183], v[212:215], v[0:3]
	v_mfma_f32_16x16x32_bf16 v[58:61], v[176:179], v[192:195], v[58:61]
	v_mfma_f32_16x16x32_bf16 v[50:53], v[184:187], v[192:195], v[50:53]
	v_mfma_f32_16x16x32_bf16 v[42:45], v[176:179], v[200:203], v[42:45]
	v_mfma_f32_16x16x32_bf16 v[34:37], v[184:187], v[200:203], v[34:37]
	v_mfma_f32_16x16x32_bf16 v[24:27], v[176:179], v[208:211], v[24:27]
	v_mfma_f32_16x16x32_bf16 v[16:19], v[184:187], v[208:211], v[16:19]
	v_mfma_f32_16x16x32_bf16 v[8:11], v[176:179], v[220:223], v[8:11]
	v_mfma_f32_16x16x32_bf16 v[0:3], v[184:187], v[220:223], v[0:3]
	s_barrier
	s_add_i32 s27, s27, 2
	s_add_u32 s62, s62, 0x100
	s_addc_u32 s63, s63, 0
	s_add_u32 s18, s18, 0x100
	s_addc_u32 s19, s19, 0
	s_cmp_gt_u32 s27, 13
	s_cbranch_scc0 .LBB0_202
	s_and_b64 vcc, exec, s[24:25]
	s_cbranch_vccz .LBB0_205
	s_barrier

.LBB0_333:
	s_add_i32 s66, s52, 2
	s_add_u32 s53, s50, 0xfffc0080
	s_addc_u32 s54, s51, -1
	s_add_i32 s67, 0, 0x10000
	s_cmp_eq_u32 s27, s52
	s_cselect_b32 s55, s18, s54
	s_cselect_b32 s54, s19, s53
	v_add_u32_e32 v140, s67, v143
	s_cselect_b32 s53, s22, s65
	s_cselect_b32 s52, s23, s64
	s_add_i32 s69, 0, 0x14000
	ds_read_b128 v[146:149], v140
	ds_read_b128 v[150:153], v140 offset:1024
	ds_read_b128 v[154:157], v140 offset:2048
	ds_read_b128 v[158:161], v140 offset:3072
	v_add_u32_e32 v140, s69, v143
	ds_read_b128 v[162:165], v140
	ds_read_b128 v[176:179], v140 offset:1024
	ds_read_b128 v[180:183], v140 offset:2048
	ds_read_b128 v[184:187], v140 offset:3072
	v_lshl_add_u64 v[140:141], s[50:51], 0, v[136:137]
	s_add_i32 m0, s33, 0xc000
	ds_read_b128 v[188:191], v144
	ds_read_b128 v[192:195], v144 offset:1024
	ds_read_b128 v[196:199], v144 offset:2048
	ds_read_b128 v[200:203], v144 offset:3072
	ds_read_b128 v[204:207], v144 offset:4096
	ds_read_b128 v[208:211], v144 offset:5120
	ds_read_b128 v[212:215], v144 offset:6144
	ds_read_b128 v[220:223], v144 offset:7168
	global_load_lds_dwordx4 v[140:141], off
	v_lshl_add_u64 v[140:141], s[50:51], 0, v[138:139]
	s_add_i32 m0, s33, 0xe000
	s_nop 0
	global_load_lds_dwordx4 v[140:141], off
	s_waitcnt vmcnt(8)
	s_waitcnt lgkmcnt(0)
	s_barrier
	s_waitcnt lgkmcnt(0)
	v_mfma_f32_16x16x32_bf16 v[126:129], v[146:149], v[188:191], v[126:129]
	v_mfma_f32_16x16x32_bf16 v[122:125], v[154:157], v[188:191], v[122:125]
	v_mfma_f32_16x16x32_bf16 v[118:121], v[146:149], v[196:199], v[118:121]
	v_mfma_f32_16x16x32_bf16 v[110:113], v[154:157], v[196:199], v[110:113]
	v_mfma_f32_16x16x32_bf16 v[102:105], v[146:149], v[204:207], v[102:105]
	v_mfma_f32_16x16x32_bf16 v[94:97], v[154:157], v[204:207], v[94:97]
	v_mfma_f32_16x16x32_bf16 v[86:89], v[146:149], v[212:215], v[86:89]
	v_mfma_f32_16x16x32_bf16 v[78:81], v[154:157], v[212:215], v[78:81]
	v_mfma_f32_16x16x32_bf16 v[126:129], v[150:153], v[192:195], v[126:129]
	v_mfma_f32_16x16x32_bf16 v[122:125], v[158:161], v[192:195], v[122:125]
	v_mfma_f32_16x16x32_bf16 v[118:121], v[150:153], v[200:203], v[118:121]
	v_mfma_f32_16x16x32_bf16 v[110:113], v[158:161], v[200:203], v[110:113]
	v_mfma_f32_16x16x32_bf16 v[102:105], v[150:153], v[208:211], v[102:105]
	v_mfma_f32_16x16x32_bf16 v[94:97], v[158:161], v[208:211], v[94:97]
	v_mfma_f32_16x16x32_bf16 v[86:89], v[150:153], v[220:223], v[86:89]
	v_mfma_f32_16x16x32_bf16 v[78:81], v[158:161], v[220:223], v[78:81]
	v_mfma_f32_16x16x32_bf16 v[114:117], v[162:165], v[188:191], v[114:117]
	v_mfma_f32_16x16x32_bf16 v[106:109], v[180:183], v[188:191], v[106:109]
	v_mfma_f32_16x16x32_bf16 v[98:101], v[162:165], v[196:199], v[98:101]
	v_mfma_f32_16x16x32_bf16 v[90:93], v[180:183], v[196:199], v[90:93]
	v_mfma_f32_16x16x32_bf16 v[82:85], v[162:165], v[204:207], v[82:85]
	v_mfma_f32_16x16x32_bf16 v[74:77], v[180:183], v[204:207], v[74:77]
	v_mfma_f32_16x16x32_bf16 v[70:73], v[162:165], v[212:215], v[70:73]
	v_mfma_f32_16x16x32_bf16 v[66:69], v[180:183], v[212:215], v[66:69]
	v_mfma_f32_16x16x32_bf16 v[114:117], v[176:179], v[192:195], v[114:117]
	v_mfma_f32_16x16x32_bf16 v[106:109], v[184:187], v[192:195], v[106:109]
	v_mfma_f32_16x16x32_bf16 v[98:101], v[176:179], v[200:203], v[98:101]
	v_mfma_f32_16x16x32_bf16 v[90:93], v[184:187], v[200:203], v[90:93]
	v_mfma_f32_16x16x32_bf16 v[82:85], v[176:179], v[208:211], v[82:85]
	v_mfma_f32_16x16x32_bf16 v[74:77], v[184:187], v[208:211], v[74:77]
	v_mfma_f32_16x16x32_bf16 v[70:73], v[176:179], v[220:223], v[70:73]
	v_mfma_f32_16x16x32_bf16 v[66:69], v[184:187], v[220:223], v[66:69]
	s_barrier
	s_add_i32 s67, s67, s13
	v_lshl_add_u64 v[140:141], s[52:53], 0, v[32:33]
	s_mov_b32 m0, s67
	ds_read_b128 v[188:191], v144 offset:16384
	ds_read_b128 v[192:195], v144 offset:17408
	ds_read_b128 v[196:199], v144 offset:18432
	ds_read_b128 v[200:203], v144 offset:19456
	ds_read_b128 v[204:207], v144 offset:20480
	ds_read_b128 v[208:211], v144 offset:21504
	ds_read_b128 v[212:215], v144 offset:22528
	ds_read_b128 v[220:223], v144 offset:23552
	global_load_lds_dwordx4 v[140:141], off
	s_add_i32 m0, s67, 0x2000
	s_add_u32 s78, s52, 0x40000
	v_lshl_add_u64 v[224:225], s[52:53], 0, v[134:135]
	s_addc_u32 s79, s53, 0
	s_add_i32 s67, s69, s13
	global_load_lds_dwordx4 v[224:225], off
	v_lshl_add_u64 v[226:227], s[78:79], 0, v[32:33]
	s_mov_b32 m0, s67
	v_lshl_add_u64 v[228:229], s[54:55], 0, v[132:133]
	global_load_lds_dwordx4 v[226:227], off
	v_lshl_add_u64 v[226:227], s[78:79], 0, v[134:135]
	s_add_i32 m0, s67, 0x2000
	s_nop 0
	global_load_lds_dwordx4 v[226:227], off
	v_lshl_add_u64 v[226:227], s[54:55], 0, v[130:131]
	s_mov_b32 m0, s33
	s_nop 0
	global_load_lds_dwordx4 v[226:227], off
	s_mov_b32 m0, s38
	s_nop 0
	global_load_lds_dwordx4 v[228:229], off
	s_waitcnt vmcnt(8)
	s_waitcnt lgkmcnt(0)
	s_barrier
	s_waitcnt lgkmcnt(0)
	v_mfma_f32_16x16x32_bf16 v[62:65], v[146:149], v[188:191], v[62:65]
	v_mfma_f32_16x16x32_bf16 v[58:61], v[154:157], v[188:191], v[58:61]
	v_mfma_f32_16x16x32_bf16 v[54:57], v[146:149], v[196:199], v[54:57]
	v_mfma_f32_16x16x32_bf16 v[46:49], v[154:157], v[196:199], v[46:49]
	v_mfma_f32_16x16x32_bf16 v[38:41], v[146:149], v[204:207], v[38:41]
	v_mfma_f32_16x16x32_bf16 v[28:31], v[154:157], v[204:207], v[28:31]
	v_mfma_f32_16x16x32_bf16 v[20:23], v[146:149], v[212:215], v[20:23]
	v_mfma_f32_16x16x32_bf16 v[12:15], v[154:157], v[212:215], v[12:15]
	v_mfma_f32_16x16x32_bf16 v[62:65], v[150:153], v[192:195], v[62:65]
	v_mfma_f32_16x16x32_bf16 v[58:61], v[158:161], v[192:195], v[58:61]
	v_mfma_f32_16x16x32_bf16 v[54:57], v[150:153], v[200:203], v[54:57]
	v_mfma_f32_16x16x32_bf16 v[46:49], v[158:161], v[200:203], v[46:49]
	v_mfma_f32_16x16x32_bf16 v[38:41], v[150:153], v[208:211], v[38:41]
	v_mfma_f32_16x16x32_bf16 v[28:31], v[158:161], v[208:211], v[28:31]
	v_mfma_f32_16x16x32_bf16 v[20:23], v[150:153], v[220:223], v[20:23]
	v_mfma_f32_16x16x32_bf16 v[12:15], v[158:161], v[220:223], v[12:15]
	v_mfma_f32_16x16x32_bf16 v[50:53], v[162:165], v[188:191], v[50:53]
	v_mfma_f32_16x16x32_bf16 v[42:45], v[180:183], v[188:191], v[42:45]
	v_mfma_f32_16x16x32_bf16 v[34:37], v[162:165], v[196:199], v[34:37]
	v_mfma_f32_16x16x32_bf16 v[24:27], v[180:183], v[196:199], v[24:27]
	v_mfma_f32_16x16x32_bf16 v[16:19], v[162:165], v[204:207], v[16:19]
	v_mfma_f32_16x16x32_bf16 v[8:11], v[180:183], v[204:207], v[8:11]
	v_mfma_f32_16x16x32_bf16 v[4:7], v[162:165], v[212:215], v[4:7]
	v_mfma_f32_16x16x32_bf16 v[0:3], v[180:183], v[212:215], v[0:3]
	v_mfma_f32_16x16x32_bf16 v[50:53], v[176:179], v[192:195], v[50:53]
	v_mfma_f32_16x16x32_bf16 v[42:45], v[184:187], v[192:195], v[42:45]
	v_mfma_f32_16x16x32_bf16 v[34:37], v[176:179], v[200:203], v[34:37]
	v_mfma_f32_16x16x32_bf16 v[24:27], v[184:187], v[200:203], v[24:27]
	v_mfma_f32_16x16x32_bf16 v[16:19], v[176:179], v[208:211], v[16:19]
	v_mfma_f32_16x16x32_bf16 v[8:11], v[184:187], v[208:211], v[8:11]
	v_mfma_f32_16x16x32_bf16 v[4:7], v[176:179], v[220:223], v[4:7]
	v_mfma_f32_16x16x32_bf16 v[0:3], v[184:187], v[220:223], v[0:3]
	s_barrier
	s_add_i32 s67, 0, 0x18000
	v_add_u32_e32 v145, s67, v143
	s_add_i32 s69, 0, 0x1c000
	ds_read_b128 v[146:149], v145
	ds_read_b128 v[150:153], v145 offset:1024
	ds_read_b128 v[154:157], v145 offset:2048
	ds_read_b128 v[158:161], v145 offset:3072
	v_add_u32_e32 v145, s69, v143
	ds_read_b128 v[162:165], v145
	ds_read_b128 v[176:179], v145 offset:1024
	ds_read_b128 v[180:183], v145 offset:2048
	ds_read_b128 v[184:187], v145 offset:3072
	s_add_u32 s54, s54, 0x40000
	s_addc_u32 s55, s55, 0
	s_mov_b32 m0, s39
	v_lshl_add_u64 v[230:231], s[54:55], 0, v[130:131]
	ds_read_b128 v[188:191], v144 offset:32768
	ds_read_b128 v[192:195], v144 offset:33792
	ds_read_b128 v[196:199], v144 offset:34816
	ds_read_b128 v[200:203], v144 offset:35840
	ds_read_b128 v[204:207], v144 offset:36864
	ds_read_b128 v[208:211], v144 offset:37888
	ds_read_b128 v[212:215], v144 offset:38912
	ds_read_b128 v[220:223], v144 offset:39936
	global_load_lds_dwordx4 v[230:231], off
	v_lshl_add_u64 v[230:231], s[54:55], 0, v[132:133]
	s_mov_b32 m0, s46
	s_nop 0
	global_load_lds_dwordx4 v[230:231], off
	s_waitcnt vmcnt(8)
	s_waitcnt lgkmcnt(0)
	s_barrier
	s_waitcnt lgkmcnt(0)
	v_mfma_f32_16x16x32_bf16 v[126:129], v[146:149], v[188:191], v[126:129]
	v_mfma_f32_16x16x32_bf16 v[122:125], v[154:157], v[188:191], v[122:125]
	v_mfma_f32_16x16x32_bf16 v[118:121], v[146:149], v[196:199], v[118:121]
	v_mfma_f32_16x16x32_bf16 v[110:113], v[154:157], v[196:199], v[110:113]
	v_mfma_f32_16x16x32_bf16 v[102:105], v[146:149], v[204:207], v[102:105]
	v_mfma_f32_16x16x32_bf16 v[94:97], v[154:157], v[204:207], v[94:97]
	v_mfma_f32_16x16x32_bf16 v[86:89], v[146:149], v[212:215], v[86:89]
	v_mfma_f32_16x16x32_bf16 v[78:81], v[154:157], v[212:215], v[78:81]
	v_mfma_f32_16x16x32_bf16 v[126:129], v[150:153], v[192:195], v[126:129]
	v_mfma_f32_16x16x32_bf16 v[122:125], v[158:161], v[192:195], v[122:125]
	v_mfma_f32_16x16x32_bf16 v[118:121], v[150:153], v[200:203], v[118:121]
	v_mfma_f32_16x16x32_bf16 v[110:113], v[158:161], v[200:203], v[110:113]
	v_mfma_f32_16x16x32_bf16 v[102:105], v[150:153], v[208:211], v[102:105]
	v_mfma_f32_16x16x32_bf16 v[94:97], v[158:161], v[208:211], v[94:97]
	v_mfma_f32_16x16x32_bf16 v[86:89], v[150:153], v[220:223], v[86:89]
	v_mfma_f32_16x16x32_bf16 v[78:81], v[158:161], v[220:223], v[78:81]
	v_mfma_f32_16x16x32_bf16 v[114:117], v[162:165], v[188:191], v[114:117]
	v_mfma_f32_16x16x32_bf16 v[106:109], v[180:183], v[188:191], v[106:109]
	v_mfma_f32_16x16x32_bf16 v[98:101], v[162:165], v[196:199], v[98:101]
	v_mfma_f32_16x16x32_bf16 v[90:93], v[180:183], v[196:199], v[90:93]
	v_mfma_f32_16x16x32_bf16 v[82:85], v[162:165], v[204:207], v[82:85]
	v_mfma_f32_16x16x32_bf16 v[74:77], v[180:183], v[204:207], v[74:77]
	v_mfma_f32_16x16x32_bf16 v[70:73], v[162:165], v[212:215], v[70:73]
	v_mfma_f32_16x16x32_bf16 v[66:69], v[180:183], v[212:215], v[66:69]
	v_mfma_f32_16x16x32_bf16 v[114:117], v[176:179], v[192:195], v[114:117]
	v_mfma_f32_16x16x32_bf16 v[106:109], v[184:187], v[192:195], v[106:109]
	v_mfma_f32_16x16x32_bf16 v[98:101], v[176:179], v[200:203], v[98:101]
	v_mfma_f32_16x16x32_bf16 v[90:93], v[184:187], v[200:203], v[90:93]
	v_mfma_f32_16x16x32_bf16 v[82:85], v[176:179], v[208:211], v[82:85]
	v_mfma_f32_16x16x32_bf16 v[74:77], v[184:187], v[208:211], v[74:77]
	v_mfma_f32_16x16x32_bf16 v[70:73], v[176:179], v[220:223], v[70:73]
	v_mfma_f32_16x16x32_bf16 v[66:69], v[184:187], v[220:223], v[66:69]
	s_barrier
	s_add_i32 s54, s67, s13
	v_lshl_add_u64 v[140:141], v[140:141], 0, s[28:29]
	s_mov_b32 m0, s54
	ds_read_b128 v[188:191], v144 offset:49152
	ds_read_b128 v[192:195], v144 offset:50176
	ds_read_b128 v[196:199], v144 offset:51200
	ds_read_b128 v[200:203], v144 offset:52224
	ds_read_b128 v[204:207], v144 offset:53248
	ds_read_b128 v[208:211], v144 offset:54272
	ds_read_b128 v[212:215], v144 offset:55296
	ds_read_b128 v[220:223], v144 offset:56320
	global_load_lds_dwordx4 v[140:141], off
	s_add_i32 m0, s54, 0x2000
	s_add_u32 s52, s52, 0x40080
	v_lshl_add_u64 v[140:141], v[224:225], 0, s[28:29]
	s_addc_u32 s53, s53, 0
	s_add_i32 s54, s69, s13
	global_load_lds_dwordx4 v[140:141], off
	v_lshl_add_u64 v[140:141], s[52:53], 0, v[32:33]
	s_mov_b32 m0, s54
	s_nop 0
	global_load_lds_dwordx4 v[140:141], off
	v_lshl_add_u64 v[140:141], s[52:53], 0, v[134:135]
	s_add_i32 m0, s54, 0x2000
	s_nop 0
	global_load_lds_dwordx4 v[140:141], off
	v_lshl_add_u64 v[140:141], v[226:227], 0, s[28:29]
	s_mov_b32 m0, s57
	s_nop 0
	global_load_lds_dwordx4 v[140:141], off
	v_lshl_add_u64 v[140:141], v[228:229], 0, s[28:29]
	s_mov_b32 m0, s58
	s_nop 0
	global_load_lds_dwordx4 v[140:141], off
	s_waitcnt vmcnt(8)
	s_waitcnt lgkmcnt(0)
	s_barrier
	s_waitcnt lgkmcnt(0)
	v_mfma_f32_16x16x32_bf16 v[62:65], v[146:149], v[188:191], v[62:65]
	v_mfma_f32_16x16x32_bf16 v[58:61], v[154:157], v[188:191], v[58:61]
	v_mfma_f32_16x16x32_bf16 v[54:57], v[146:149], v[196:199], v[54:57]
	v_mfma_f32_16x16x32_bf16 v[46:49], v[154:157], v[196:199], v[46:49]
	v_mfma_f32_16x16x32_bf16 v[38:41], v[146:149], v[204:207], v[38:41]
	v_mfma_f32_16x16x32_bf16 v[28:31], v[154:157], v[204:207], v[28:31]
	v_mfma_f32_16x16x32_bf16 v[20:23], v[146:149], v[212:215], v[20:23]
	v_mfma_f32_16x16x32_bf16 v[12:15], v[154:157], v[212:215], v[12:15]
	v_mfma_f32_16x16x32_bf16 v[62:65], v[150:153], v[192:195], v[62:65]
	v_mfma_f32_16x16x32_bf16 v[58:61], v[158:161], v[192:195], v[58:61]
	v_mfma_f32_16x16x32_bf16 v[54:57], v[150:153], v[200:203], v[54:57]
	v_mfma_f32_16x16x32_bf16 v[46:49], v[158:161], v[200:203], v[46:49]
	v_mfma_f32_16x16x32_bf16 v[38:41], v[150:153], v[208:211], v[38:41]
	v_mfma_f32_16x16x32_bf16 v[28:31], v[158:161], v[208:211], v[28:31]
	v_mfma_f32_16x16x32_bf16 v[20:23], v[150:153], v[220:223], v[20:23]
	v_mfma_f32_16x16x32_bf16 v[12:15], v[158:161], v[220:223], v[12:15]
	v_mfma_f32_16x16x32_bf16 v[50:53], v[162:165], v[188:191], v[50:53]
	v_mfma_f32_16x16x32_bf16 v[42:45], v[180:183], v[188:191], v[42:45]
	v_mfma_f32_16x16x32_bf16 v[34:37], v[162:165], v[196:199], v[34:37]
	v_mfma_f32_16x16x32_bf16 v[24:27], v[180:183], v[196:199], v[24:27]
	v_mfma_f32_16x16x32_bf16 v[16:19], v[162:165], v[204:207], v[16:19]
	v_mfma_f32_16x16x32_bf16 v[8:11], v[180:183], v[204:207], v[8:11]
	v_mfma_f32_16x16x32_bf16 v[4:7], v[162:165], v[212:215], v[4:7]
	v_mfma_f32_16x16x32_bf16 v[0:3], v[180:183], v[212:215], v[0:3]
	v_mfma_f32_16x16x32_bf16 v[50:53], v[176:179], v[192:195], v[50:53]
	v_mfma_f32_16x16x32_bf16 v[42:45], v[184:187], v[192:195], v[42:45]
	v_mfma_f32_16x16x32_bf16 v[34:37], v[176:179], v[200:203], v[34:37]
	v_mfma_f32_16x16x32_bf16 v[24:27], v[184:187], v[200:203], v[24:27]
	v_mfma_f32_16x16x32_bf16 v[16:19], v[176:179], v[208:211], v[16:19]
	v_mfma_f32_16x16x32_bf16 v[8:11], v[184:187], v[208:211], v[8:11]
	v_mfma_f32_16x16x32_bf16 v[4:7], v[176:179], v[220:223], v[4:7]
	v_mfma_f32_16x16x32_bf16 v[0:3], v[184:187], v[220:223], v[0:3]
	s_barrier
	s_add_u32 s50, s50, 0x100
	s_addc_u32 s51, s51, 0
	s_add_u32 s64, s64, 0x100
	s_addc_u32 s65, s65, 0
	s_cmp_ge_i32 s66, s61
	s_mov_b32 s52, s66
	s_cbranch_scc0 .LBB0_333
	s_and_b64 vcc, exec, s[20:21]
	s_cbranch_vccz .LBB0_336
	s_barrier

.LBB0_381:
	s_add_i32 s42, s24, 2
	s_add_u32 s0, s20, 0xfffc0080
	s_addc_u32 s25, s21, -1
	s_add_i32 s90, 0, 0x10000
	s_cmp_eq_u32 s1, s24
	s_cselect_b32 s27, s61, s25
	s_cselect_b32 s26, s60, s0
	s_cselect_b32 s25, s63, s23
	s_cselect_b32 s24, s62, s22
	s_add_i32 s33, 0, 0x14000
	v_add_u32_e32 v172, s90, v169
	v_add_u32_e32 v174, s33, v169
	ds_read_b128 v[130:133], v172
	ds_read_b128 v[134:137], v172 offset:1024
	ds_read_b128 v[152:155], v172 offset:2048
	ds_read_b128 v[156:159], v172 offset:3072
	ds_read_b128 v[160:163], v174
	ds_read_b128 v[176:179], v174 offset:1024
	ds_read_b128 v[180:183], v174 offset:2048
	ds_read_b128 v[184:187], v174 offset:3072
	s_add_i32 s59, s77, 0xc000
	v_lshl_add_u64 v[164:165], s[20:21], 0, v[144:145]
	s_mov_b32 m0, s59
	s_add_i32 s89, s77, 0xe000
	ds_read_b128 v[188:191], v170
	ds_read_b128 v[192:195], v170 offset:1024
	ds_read_b128 v[196:199], v170 offset:2048
	ds_read_b128 v[200:203], v170 offset:3072
	ds_read_b128 v[204:207], v170 offset:4096
	ds_read_b128 v[208:211], v170 offset:5120
	ds_read_b128 v[212:215], v170 offset:6144
	ds_read_b128 v[220:223], v170 offset:7168
	global_load_lds_dwordx4 v[164:165], off
	v_lshl_add_u64 v[164:165], s[20:21], 0, v[146:147]
	s_mov_b32 m0, s89
	s_nop 0
	global_load_lds_dwordx4 v[164:165], off
	s_waitcnt vmcnt(8)
	s_waitcnt lgkmcnt(0)
	s_barrier
	s_waitcnt lgkmcnt(0)
	v_mfma_f32_16x16x32_bf16 v[0:3], v[130:133], v[188:191], v[0:3]
	v_mfma_f32_16x16x32_bf16 v[4:7], v[152:155], v[188:191], v[4:7]
	v_mfma_f32_16x16x32_bf16 v[16:19], v[130:133], v[196:199], v[16:19]
	v_mfma_f32_16x16x32_bf16 v[20:23], v[152:155], v[196:199], v[20:23]
	v_mfma_f32_16x16x32_bf16 v[46:49], v[130:133], v[204:207], v[46:49]
	v_mfma_f32_16x16x32_bf16 v[50:53], v[152:155], v[204:207], v[50:53]
	v_mfma_f32_16x16x32_bf16 v[66:69], v[130:133], v[212:215], v[66:69]
	v_mfma_f32_16x16x32_bf16 v[70:73], v[152:155], v[212:215], v[70:73]
	v_mfma_f32_16x16x32_bf16 v[0:3], v[134:137], v[192:195], v[0:3]
	v_mfma_f32_16x16x32_bf16 v[4:7], v[156:159], v[192:195], v[4:7]
	v_mfma_f32_16x16x32_bf16 v[16:19], v[134:137], v[200:203], v[16:19]
	v_mfma_f32_16x16x32_bf16 v[20:23], v[156:159], v[200:203], v[20:23]
	v_mfma_f32_16x16x32_bf16 v[46:49], v[134:137], v[208:211], v[46:49]
	v_mfma_f32_16x16x32_bf16 v[50:53], v[156:159], v[208:211], v[50:53]
	v_mfma_f32_16x16x32_bf16 v[66:69], v[134:137], v[220:223], v[66:69]
	v_mfma_f32_16x16x32_bf16 v[70:73], v[156:159], v[220:223], v[70:73]
	v_mfma_f32_16x16x32_bf16 v[8:11], v[160:163], v[188:191], v[8:11]
	v_mfma_f32_16x16x32_bf16 v[12:15], v[180:183], v[188:191], v[12:15]
	v_mfma_f32_16x16x32_bf16 v[24:27], v[160:163], v[196:199], v[24:27]
	v_mfma_f32_16x16x32_bf16 v[28:31], v[180:183], v[196:199], v[28:31]
	v_mfma_f32_16x16x32_bf16 v[54:57], v[160:163], v[204:207], v[54:57]
	v_mfma_f32_16x16x32_bf16 v[58:61], v[180:183], v[204:207], v[58:61]
	v_mfma_f32_16x16x32_bf16 v[74:77], v[160:163], v[212:215], v[74:77]
	v_mfma_f32_16x16x32_bf16 v[78:81], v[180:183], v[212:215], v[78:81]
	v_mfma_f32_16x16x32_bf16 v[8:11], v[176:179], v[192:195], v[8:11]
	v_mfma_f32_16x16x32_bf16 v[12:15], v[184:187], v[192:195], v[12:15]
	v_mfma_f32_16x16x32_bf16 v[24:27], v[176:179], v[200:203], v[24:27]
	v_mfma_f32_16x16x32_bf16 v[28:31], v[184:187], v[200:203], v[28:31]
	v_mfma_f32_16x16x32_bf16 v[54:57], v[176:179], v[208:211], v[54:57]
	v_mfma_f32_16x16x32_bf16 v[58:61], v[184:187], v[208:211], v[58:61]
	v_mfma_f32_16x16x32_bf16 v[74:77], v[176:179], v[220:223], v[74:77]
	v_mfma_f32_16x16x32_bf16 v[78:81], v[184:187], v[220:223], v[78:81]
	s_barrier
	s_add_i32 s90, s90, s69
	s_add_i32 s91, s90, 0x2000
	v_lshl_add_u64 v[164:165], s[24:25], 0, v[32:33]
	s_mov_b32 m0, s90
	s_add_u32 s38, s24, 0x40000
	ds_read_b128 v[188:191], v170 offset:16384
	ds_read_b128 v[192:195], v170 offset:17408
	ds_read_b128 v[196:199], v170 offset:18432
	ds_read_b128 v[200:203], v170 offset:19456
	ds_read_b128 v[204:207], v170 offset:20480
	ds_read_b128 v[208:211], v170 offset:21504
	ds_read_b128 v[212:215], v170 offset:22528
	ds_read_b128 v[220:223], v170 offset:23552
	global_load_lds_dwordx4 v[164:165], off
	v_lshl_add_u64 v[228:229], s[24:25], 0, v[142:143]
	s_mov_b32 m0, s91
	s_addc_u32 s39, s25, 0
	s_add_i32 s33, s33, s69
	global_load_lds_dwordx4 v[228:229], off
	v_lshl_add_u64 v[224:225], s[38:39], 0, v[32:33]
	s_mov_b32 m0, s33
	v_lshl_add_u64 v[230:231], s[26:27], 0, v[138:139]
	global_load_lds_dwordx4 v[224:225], off
	v_lshl_add_u64 v[224:225], s[38:39], 0, v[142:143]
	s_add_i32 s38, s33, 0x2000
	s_mov_b32 m0, s38
	v_lshl_add_u64 v[232:233], s[26:27], 0, v[140:141]
	global_load_lds_dwordx4 v[224:225], off
	s_mov_b32 m0, s77
	s_nop 0
	global_load_lds_dwordx4 v[230:231], off
	s_mov_b32 m0, s13
	s_nop 0
	global_load_lds_dwordx4 v[232:233], off
	s_waitcnt vmcnt(8)
	s_waitcnt lgkmcnt(0)
	s_barrier
	s_waitcnt lgkmcnt(0)
	v_mfma_f32_16x16x32_bf16 v[82:85], v[130:133], v[188:191], v[82:85]
	v_mfma_f32_16x16x32_bf16 v[86:89], v[152:155], v[188:191], v[86:89]
	v_mfma_f32_16x16x32_bf16 v[106:109], v[130:133], v[196:199], v[106:109]
	v_mfma_f32_16x16x32_bf16 v[114:117], v[152:155], v[196:199], v[114:117]
	v_mfma_f32_16x16x32_bf16 v[126:129], v[130:133], v[204:207], v[126:129]
	v_mfma_f32_16x16x32_bf16 v[110:113], v[152:155], v[204:207], v[110:113]
	v_mfma_f32_16x16x32_bf16 v[62:65], v[130:133], v[212:215], v[62:65]
	v_mfma_f32_16x16x32_bf16 v[42:45], v[152:155], v[212:215], v[42:45]
	v_mfma_f32_16x16x32_bf16 v[82:85], v[134:137], v[192:195], v[82:85]
	v_mfma_f32_16x16x32_bf16 v[86:89], v[156:159], v[192:195], v[86:89]
	v_mfma_f32_16x16x32_bf16 v[106:109], v[134:137], v[200:203], v[106:109]
	v_mfma_f32_16x16x32_bf16 v[114:117], v[156:159], v[200:203], v[114:117]
	v_mfma_f32_16x16x32_bf16 v[126:129], v[134:137], v[208:211], v[126:129]
	v_mfma_f32_16x16x32_bf16 v[110:113], v[156:159], v[208:211], v[110:113]
	v_mfma_f32_16x16x32_bf16 v[62:65], v[134:137], v[220:223], v[62:65]
	v_mfma_f32_16x16x32_bf16 v[42:45], v[156:159], v[220:223], v[42:45]
	v_mfma_f32_16x16x32_bf16 v[90:93], v[160:163], v[188:191], v[90:93]
	v_mfma_f32_16x16x32_bf16 v[94:97], v[180:183], v[188:191], v[94:97]
	v_mfma_f32_16x16x32_bf16 v[118:121], v[160:163], v[196:199], v[118:121]
	v_mfma_f32_16x16x32_bf16 v[122:125], v[180:183], v[196:199], v[122:125]
	v_mfma_f32_16x16x32_bf16 v[102:105], v[160:163], v[204:207], v[102:105]
	v_mfma_f32_16x16x32_bf16 v[98:101], v[180:183], v[204:207], v[98:101]
	v_mfma_f32_16x16x32_bf16 v[38:41], v[160:163], v[212:215], v[38:41]
	v_mfma_f32_16x16x32_bf16 v[34:37], v[180:183], v[212:215], v[34:37]
	v_mfma_f32_16x16x32_bf16 v[90:93], v[176:179], v[192:195], v[90:93]
	v_mfma_f32_16x16x32_bf16 v[94:97], v[184:187], v[192:195], v[94:97]
	v_mfma_f32_16x16x32_bf16 v[118:121], v[176:179], v[200:203], v[118:121]
	v_mfma_f32_16x16x32_bf16 v[122:125], v[184:187], v[200:203], v[122:125]
	v_mfma_f32_16x16x32_bf16 v[102:105], v[176:179], v[208:211], v[102:105]
	v_mfma_f32_16x16x32_bf16 v[98:101], v[184:187], v[208:211], v[98:101]
	v_mfma_f32_16x16x32_bf16 v[38:41], v[176:179], v[220:223], v[38:41]
	v_mfma_f32_16x16x32_bf16 v[34:37], v[184:187], v[220:223], v[34:37]
	s_barrier
	s_add_i32 s39, 0, 0x18000
	s_add_i32 s65, 0, 0x1c000
	v_add_u32_e32 v176, s39, v169
	v_add_u32_e32 v177, s65, v169
	ds_read_b128 v[130:133], v176
	ds_read_b128 v[134:137], v176 offset:1024
	ds_read_b128 v[152:155], v176 offset:2048
	ds_read_b128 v[156:159], v176 offset:3072
	ds_read_b128 v[160:163], v177
	ds_read_b128 v[178:181], v177 offset:1024
	ds_read_b128 v[182:185], v177 offset:2048
	ds_read_b128 v[186:189], v177 offset:3072
	s_add_u32 s26, s26, 0x40000
	s_addc_u32 s27, s27, 0
	s_mov_b32 m0, s78
	v_lshl_add_u64 v[214:215], s[26:27], 0, v[138:139]
	ds_read_b128 v[190:193], v170 offset:32768
	ds_read_b128 v[194:197], v170 offset:33792
	ds_read_b128 v[198:201], v170 offset:34816
	ds_read_b128 v[202:205], v170 offset:35840
	ds_read_b128 v[206:209], v170 offset:36864
	ds_read_b128 v[210:213], v170 offset:37888
	ds_read_b128 v[220:223], v170 offset:38912
	ds_read_b128 v[224:227], v170 offset:39936
	global_load_lds_dwordx4 v[214:215], off
	v_lshl_add_u64 v[214:215], s[26:27], 0, v[140:141]
	s_mov_b32 m0, s12
	s_nop 0
	global_load_lds_dwordx4 v[214:215], off
	s_waitcnt vmcnt(8)
	s_waitcnt lgkmcnt(0)
	s_barrier
	s_waitcnt lgkmcnt(0)
	v_mfma_f32_16x16x32_bf16 v[0:3], v[130:133], v[190:193], v[0:3]
	v_mfma_f32_16x16x32_bf16 v[4:7], v[152:155], v[190:193], v[4:7]
	v_mfma_f32_16x16x32_bf16 v[16:19], v[130:133], v[198:201], v[16:19]
	v_mfma_f32_16x16x32_bf16 v[20:23], v[152:155], v[198:201], v[20:23]
	v_mfma_f32_16x16x32_bf16 v[46:49], v[130:133], v[206:209], v[46:49]
	v_mfma_f32_16x16x32_bf16 v[50:53], v[152:155], v[206:209], v[50:53]
	v_mfma_f32_16x16x32_bf16 v[66:69], v[130:133], v[220:223], v[66:69]
	v_mfma_f32_16x16x32_bf16 v[70:73], v[152:155], v[220:223], v[70:73]
	v_mfma_f32_16x16x32_bf16 v[0:3], v[134:137], v[194:197], v[0:3]
	v_mfma_f32_16x16x32_bf16 v[4:7], v[156:159], v[194:197], v[4:7]
	v_mfma_f32_16x16x32_bf16 v[16:19], v[134:137], v[202:205], v[16:19]
	v_mfma_f32_16x16x32_bf16 v[20:23], v[156:159], v[202:205], v[20:23]
	v_mfma_f32_16x16x32_bf16 v[46:49], v[134:137], v[210:213], v[46:49]
	v_mfma_f32_16x16x32_bf16 v[50:53], v[156:159], v[210:213], v[50:53]
	v_mfma_f32_16x16x32_bf16 v[66:69], v[134:137], v[224:227], v[66:69]
	v_mfma_f32_16x16x32_bf16 v[70:73], v[156:159], v[224:227], v[70:73]
	v_mfma_f32_16x16x32_bf16 v[8:11], v[160:163], v[190:193], v[8:11]
	v_mfma_f32_16x16x32_bf16 v[12:15], v[182:185], v[190:193], v[12:15]
	v_mfma_f32_16x16x32_bf16 v[24:27], v[160:163], v[198:201], v[24:27]
	v_mfma_f32_16x16x32_bf16 v[28:31], v[182:185], v[198:201], v[28:31]
	v_mfma_f32_16x16x32_bf16 v[54:57], v[160:163], v[206:209], v[54:57]
	v_mfma_f32_16x16x32_bf16 v[58:61], v[182:185], v[206:209], v[58:61]
	v_mfma_f32_16x16x32_bf16 v[74:77], v[160:163], v[220:223], v[74:77]
	v_mfma_f32_16x16x32_bf16 v[78:81], v[182:185], v[220:223], v[78:81]
	v_mfma_f32_16x16x32_bf16 v[8:11], v[178:181], v[194:197], v[8:11]
	v_mfma_f32_16x16x32_bf16 v[12:15], v[186:189], v[194:197], v[12:15]
	v_mfma_f32_16x16x32_bf16 v[24:27], v[178:181], v[202:205], v[24:27]
	v_mfma_f32_16x16x32_bf16 v[28:31], v[186:189], v[202:205], v[28:31]
	v_mfma_f32_16x16x32_bf16 v[54:57], v[178:181], v[210:213], v[54:57]
	v_mfma_f32_16x16x32_bf16 v[58:61], v[186:189], v[210:213], v[58:61]
	v_mfma_f32_16x16x32_bf16 v[74:77], v[178:181], v[224:227], v[74:77]
	v_mfma_f32_16x16x32_bf16 v[78:81], v[186:189], v[224:227], v[78:81]
	s_barrier
	s_add_i32 s39, s39, s69
	s_add_i32 s64, s39, 0x2000
	v_lshl_add_u64 v[164:165], v[164:165], 0, s[28:29]
	s_mov_b32 m0, s39
	s_add_u32 s24, s24, 0x40080
	ds_read_b128 v[190:193], v170 offset:49152
	ds_read_b128 v[194:197], v170 offset:50176
	ds_read_b128 v[198:201], v170 offset:51200
	ds_read_b128 v[202:205], v170 offset:52224
	ds_read_b128 v[206:209], v170 offset:53248
	ds_read_b128 v[210:213], v170 offset:54272
	ds_read_b128 v[220:223], v170 offset:55296
	ds_read_b128 v[224:227], v170 offset:56320
	global_load_lds_dwordx4 v[164:165], off
	v_lshl_add_u64 v[164:165], v[228:229], 0, s[28:29]
	s_mov_b32 m0, s64
	s_addc_u32 s25, s25, 0
	s_add_i32 s65, s65, s69
	global_load_lds_dwordx4 v[164:165], off
	v_lshl_add_u64 v[164:165], s[24:25], 0, v[32:33]
	s_mov_b32 m0, s65
	s_add_i32 s0, s65, 0x2000
	global_load_lds_dwordx4 v[164:165], off
	v_lshl_add_u64 v[164:165], s[24:25], 0, v[142:143]
	s_mov_b32 m0, s0
	s_nop 0
	global_load_lds_dwordx4 v[164:165], off
	v_lshl_add_u64 v[164:165], v[230:231], 0, s[28:29]
	s_mov_b32 m0, s84
	s_nop 0
	global_load_lds_dwordx4 v[164:165], off
	v_lshl_add_u64 v[164:165], v[232:233], 0, s[28:29]
	s_mov_b32 m0, s85
	s_nop 0
	global_load_lds_dwordx4 v[164:165], off
	s_waitcnt vmcnt(8)
	s_waitcnt lgkmcnt(0)
	s_barrier
	s_waitcnt lgkmcnt(0)
	v_mfma_f32_16x16x32_bf16 v[82:85], v[130:133], v[190:193], v[82:85]
	v_mfma_f32_16x16x32_bf16 v[86:89], v[152:155], v[190:193], v[86:89]
	v_mfma_f32_16x16x32_bf16 v[106:109], v[130:133], v[198:201], v[106:109]
	v_mfma_f32_16x16x32_bf16 v[114:117], v[152:155], v[198:201], v[114:117]
	v_mfma_f32_16x16x32_bf16 v[126:129], v[130:133], v[206:209], v[126:129]
	v_mfma_f32_16x16x32_bf16 v[110:113], v[152:155], v[206:209], v[110:113]
	v_mfma_f32_16x16x32_bf16 v[62:65], v[130:133], v[220:223], v[62:65]
	v_mfma_f32_16x16x32_bf16 v[42:45], v[152:155], v[220:223], v[42:45]
	v_mfma_f32_16x16x32_bf16 v[82:85], v[134:137], v[194:197], v[82:85]
	v_mfma_f32_16x16x32_bf16 v[86:89], v[156:159], v[194:197], v[86:89]
	v_mfma_f32_16x16x32_bf16 v[106:109], v[134:137], v[202:205], v[106:109]
	v_mfma_f32_16x16x32_bf16 v[114:117], v[156:159], v[202:205], v[114:117]
	v_mfma_f32_16x16x32_bf16 v[126:129], v[134:137], v[210:213], v[126:129]
	v_mfma_f32_16x16x32_bf16 v[110:113], v[156:159], v[210:213], v[110:113]
	v_mfma_f32_16x16x32_bf16 v[62:65], v[134:137], v[224:227], v[62:65]
	v_mfma_f32_16x16x32_bf16 v[42:45], v[156:159], v[224:227], v[42:45]
	v_mfma_f32_16x16x32_bf16 v[90:93], v[160:163], v[190:193], v[90:93]
	v_mfma_f32_16x16x32_bf16 v[94:97], v[182:185], v[190:193], v[94:97]
	v_mfma_f32_16x16x32_bf16 v[118:121], v[160:163], v[198:201], v[118:121]
	v_mfma_f32_16x16x32_bf16 v[122:125], v[182:185], v[198:201], v[122:125]
	v_mfma_f32_16x16x32_bf16 v[102:105], v[160:163], v[206:209], v[102:105]
	v_mfma_f32_16x16x32_bf16 v[98:101], v[182:185], v[206:209], v[98:101]
	v_mfma_f32_16x16x32_bf16 v[38:41], v[160:163], v[220:223], v[38:41]
	v_mfma_f32_16x16x32_bf16 v[34:37], v[182:185], v[220:223], v[34:37]
	v_mfma_f32_16x16x32_bf16 v[90:93], v[178:181], v[194:197], v[90:93]
	v_mfma_f32_16x16x32_bf16 v[94:97], v[186:189], v[194:197], v[94:97]
	v_mfma_f32_16x16x32_bf16 v[118:121], v[178:181], v[202:205], v[118:121]
	v_mfma_f32_16x16x32_bf16 v[122:125], v[186:189], v[202:205], v[122:125]
	v_mfma_f32_16x16x32_bf16 v[102:105], v[178:181], v[210:213], v[102:105]
	v_mfma_f32_16x16x32_bf16 v[98:101], v[186:189], v[210:213], v[98:101]
	v_mfma_f32_16x16x32_bf16 v[38:41], v[178:181], v[224:227], v[38:41]
	v_mfma_f32_16x16x32_bf16 v[34:37], v[186:189], v[224:227], v[34:37]
	s_barrier
	s_add_u32 s20, s20, 0x100
	s_addc_u32 s21, s21, 0
	s_add_u32 s22, s22, 0x100
	s_addc_u32 s23, s23, 0
	s_cmp_ge_i32 s42, s79
	s_mov_b32 s24, s42
	s_cbranch_scc0 .LBB0_381
	s_and_b64 vcc, exec, s[56:57]
	s_cbranch_vccz .LBB0_384
	s_barrier

.LBB0_405:
	ds_read_b128 v[134:137], v172
	ds_read_b128 v[152:155], v172 offset:1024
	ds_read_b128 v[156:159], v172 offset:2048
	ds_read_b128 v[160:163], v172 offset:3072
	ds_read_b128 v[178:181], v174
	ds_read_b128 v[182:185], v174 offset:1024
	ds_read_b128 v[186:189], v174 offset:2048
	ds_read_b128 v[190:193], v174 offset:3072
	s_add_u32 s26, s60, s24
	s_addc_u32 s27, s61, s25
	s_add_u32 s50, s62, s24
	s_addc_u32 s51, s63, s25
	s_cmp_eq_u32 s87, s49
	s_cselect_b32 s45, s1, s27
	s_cselect_b32 s44, s22, s26
	s_cselect_b32 s27, s23, s51
	s_cselect_b32 s26, s48, s50
	s_mov_b32 m0, s59
	v_lshl_add_u64 v[164:165], s[60:61], 0, v[132:133]
	ds_read_b128 v[194:197], v170
	ds_read_b128 v[198:201], v170 offset:1024
	ds_read_b128 v[202:205], v170 offset:2048
	ds_read_b128 v[206:209], v170 offset:3072
	ds_read_b128 v[210:213], v170 offset:4096
	ds_read_b128 v[220:223], v170 offset:5120
	ds_read_b128 v[224:227], v170 offset:6144
	ds_read_b128 v[228:231], v170 offset:7168
	global_load_lds_dwordx4 v[164:165], off
	v_lshl_add_u64 v[164:165], s[60:61], 0, v[130:131]
	s_mov_b32 m0, s89
	s_nop 0
	global_load_lds_dwordx4 v[164:165], off
	s_waitcnt vmcnt(8)
	s_waitcnt lgkmcnt(0)
	s_barrier
	s_waitcnt lgkmcnt(0)
	v_mfma_f32_16x16x32_bf16 v[0:3], v[134:137], v[194:197], v[0:3]
	v_mfma_f32_16x16x32_bf16 v[4:7], v[156:159], v[194:197], v[4:7]
	v_mfma_f32_16x16x32_bf16 v[16:19], v[134:137], v[202:205], v[16:19]
	v_mfma_f32_16x16x32_bf16 v[20:23], v[156:159], v[202:205], v[20:23]
	v_mfma_f32_16x16x32_bf16 v[46:49], v[134:137], v[210:213], v[46:49]
	v_mfma_f32_16x16x32_bf16 v[50:53], v[156:159], v[210:213], v[50:53]
	v_mfma_f32_16x16x32_bf16 v[66:69], v[134:137], v[224:227], v[66:69]
	v_mfma_f32_16x16x32_bf16 v[70:73], v[156:159], v[224:227], v[70:73]
	v_mfma_f32_16x16x32_bf16 v[0:3], v[152:155], v[198:201], v[0:3]
	v_mfma_f32_16x16x32_bf16 v[4:7], v[160:163], v[198:201], v[4:7]
	v_mfma_f32_16x16x32_bf16 v[16:19], v[152:155], v[206:209], v[16:19]
	v_mfma_f32_16x16x32_bf16 v[20:23], v[160:163], v[206:209], v[20:23]
	v_mfma_f32_16x16x32_bf16 v[46:49], v[152:155], v[220:223], v[46:49]
	v_mfma_f32_16x16x32_bf16 v[50:53], v[160:163], v[220:223], v[50:53]
	v_mfma_f32_16x16x32_bf16 v[66:69], v[152:155], v[228:231], v[66:69]
	v_mfma_f32_16x16x32_bf16 v[70:73], v[160:163], v[228:231], v[70:73]
	v_mfma_f32_16x16x32_bf16 v[8:11], v[178:181], v[194:197], v[8:11]
	v_mfma_f32_16x16x32_bf16 v[12:15], v[186:189], v[194:197], v[12:15]
	v_mfma_f32_16x16x32_bf16 v[24:27], v[178:181], v[202:205], v[24:27]
	v_mfma_f32_16x16x32_bf16 v[28:31], v[186:189], v[202:205], v[28:31]
	v_mfma_f32_16x16x32_bf16 v[54:57], v[178:181], v[210:213], v[54:57]
	v_mfma_f32_16x16x32_bf16 v[58:61], v[186:189], v[210:213], v[58:61]
	v_mfma_f32_16x16x32_bf16 v[74:77], v[178:181], v[224:227], v[74:77]
	v_mfma_f32_16x16x32_bf16 v[78:81], v[186:189], v[224:227], v[78:81]
	v_mfma_f32_16x16x32_bf16 v[8:11], v[182:185], v[198:201], v[8:11]
	v_mfma_f32_16x16x32_bf16 v[12:15], v[190:193], v[198:201], v[12:15]
	v_mfma_f32_16x16x32_bf16 v[24:27], v[182:185], v[206:209], v[24:27]
	v_mfma_f32_16x16x32_bf16 v[28:31], v[190:193], v[206:209], v[28:31]
	v_mfma_f32_16x16x32_bf16 v[54:57], v[182:185], v[220:223], v[54:57]
	v_mfma_f32_16x16x32_bf16 v[58:61], v[190:193], v[220:223], v[58:61]
	v_mfma_f32_16x16x32_bf16 v[74:77], v[182:185], v[228:231], v[74:77]
	v_mfma_f32_16x16x32_bf16 v[78:81], v[190:193], v[228:231], v[78:81]
	s_barrier
	s_mov_b32 m0, s90
	v_lshl_add_u64 v[164:165], s[26:27], 0, v[32:33]
	s_add_u32 s50, s26, 0x40000
	ds_read_b128 v[194:197], v170 offset:16384
	ds_read_b128 v[198:201], v170 offset:17408
	ds_read_b128 v[202:205], v170 offset:18432
	ds_read_b128 v[206:209], v170 offset:19456
	ds_read_b128 v[210:213], v170 offset:20480
	ds_read_b128 v[220:223], v170 offset:21504
	ds_read_b128 v[224:227], v170 offset:22528
	ds_read_b128 v[228:231], v170 offset:23552
	global_load_lds_dwordx4 v[164:165], off
	v_lshl_add_u64 v[214:215], s[26:27], 0, v[142:143]
	s_mov_b32 m0, s91
	s_addc_u32 s51, s27, 0
	global_load_lds_dwordx4 v[214:215], off
	v_lshl_add_u64 v[232:233], s[50:51], 0, v[32:33]
	s_mov_b32 m0, s33
	v_lshl_add_u64 v[234:235], s[44:45], 0, v[140:141]
	global_load_lds_dwordx4 v[232:233], off
	v_lshl_add_u64 v[232:233], s[50:51], 0, v[142:143]
	s_mov_b32 m0, s38
	s_nop 0
	global_load_lds_dwordx4 v[232:233], off
	v_lshl_add_u64 v[232:233], s[44:45], 0, v[138:139]
	s_mov_b32 m0, s77
	s_nop 0
	global_load_lds_dwordx4 v[232:233], off
	s_mov_b32 m0, s13
	s_nop 0
	global_load_lds_dwordx4 v[234:235], off
	s_waitcnt vmcnt(8)
	s_waitcnt lgkmcnt(0)
	s_barrier
	s_waitcnt lgkmcnt(0)
	v_mfma_f32_16x16x32_bf16 v[82:85], v[134:137], v[194:197], v[82:85]
	v_mfma_f32_16x16x32_bf16 v[86:89], v[156:159], v[194:197], v[86:89]
	v_mfma_f32_16x16x32_bf16 v[106:109], v[134:137], v[202:205], v[106:109]
	v_mfma_f32_16x16x32_bf16 v[114:117], v[156:159], v[202:205], v[114:117]
	v_mfma_f32_16x16x32_bf16 v[126:129], v[134:137], v[210:213], v[126:129]
	v_mfma_f32_16x16x32_bf16 v[110:113], v[156:159], v[210:213], v[110:113]
	v_mfma_f32_16x16x32_bf16 v[62:65], v[134:137], v[224:227], v[62:65]
	v_mfma_f32_16x16x32_bf16 v[42:45], v[156:159], v[224:227], v[42:45]
	v_mfma_f32_16x16x32_bf16 v[82:85], v[152:155], v[198:201], v[82:85]
	v_mfma_f32_16x16x32_bf16 v[86:89], v[160:163], v[198:201], v[86:89]
	v_mfma_f32_16x16x32_bf16 v[106:109], v[152:155], v[206:209], v[106:109]
	v_mfma_f32_16x16x32_bf16 v[114:117], v[160:163], v[206:209], v[114:117]
	v_mfma_f32_16x16x32_bf16 v[126:129], v[152:155], v[220:223], v[126:129]
	v_mfma_f32_16x16x32_bf16 v[110:113], v[160:163], v[220:223], v[110:113]
	v_mfma_f32_16x16x32_bf16 v[62:65], v[152:155], v[228:231], v[62:65]
	v_mfma_f32_16x16x32_bf16 v[42:45], v[160:163], v[228:231], v[42:45]
	v_mfma_f32_16x16x32_bf16 v[90:93], v[178:181], v[194:197], v[90:93]
	v_mfma_f32_16x16x32_bf16 v[94:97], v[186:189], v[194:197], v[94:97]
	v_mfma_f32_16x16x32_bf16 v[118:121], v[178:181], v[202:205], v[118:121]
	v_mfma_f32_16x16x32_bf16 v[122:125], v[186:189], v[202:205], v[122:125]
	v_mfma_f32_16x16x32_bf16 v[102:105], v[178:181], v[210:213], v[102:105]
	v_mfma_f32_16x16x32_bf16 v[98:101], v[186:189], v[210:213], v[98:101]
	v_mfma_f32_16x16x32_bf16 v[38:41], v[178:181], v[224:227], v[38:41]
	v_mfma_f32_16x16x32_bf16 v[34:37], v[186:189], v[224:227], v[34:37]
	v_mfma_f32_16x16x32_bf16 v[90:93], v[182:185], v[198:201], v[90:93]
	v_mfma_f32_16x16x32_bf16 v[94:97], v[190:193], v[198:201], v[94:97]
	v_mfma_f32_16x16x32_bf16 v[118:121], v[182:185], v[206:209], v[118:121]
	v_mfma_f32_16x16x32_bf16 v[122:125], v[190:193], v[206:209], v[122:125]
	v_mfma_f32_16x16x32_bf16 v[102:105], v[182:185], v[220:223], v[102:105]
	v_mfma_f32_16x16x32_bf16 v[98:101], v[190:193], v[220:223], v[98:101]
	v_mfma_f32_16x16x32_bf16 v[38:41], v[182:185], v[228:231], v[38:41]
	v_mfma_f32_16x16x32_bf16 v[34:37], v[190:193], v[228:231], v[34:37]
	s_barrier
	ds_read_b128 v[134:137], v176
	ds_read_b128 v[152:155], v176 offset:1024
	ds_read_b128 v[156:159], v176 offset:2048
	ds_read_b128 v[160:163], v176 offset:3072
	ds_read_b128 v[178:181], v177
	ds_read_b128 v[182:185], v177 offset:1024
	ds_read_b128 v[186:189], v177 offset:2048
	ds_read_b128 v[190:193], v177 offset:3072
	s_add_u32 s44, s44, 0x40000
	s_addc_u32 s45, s45, 0
	s_mov_b32 m0, s78
	v_lshl_add_u64 v[236:237], s[44:45], 0, v[138:139]
	ds_read_b128 v[194:197], v170 offset:32768
	ds_read_b128 v[198:201], v170 offset:33792
	ds_read_b128 v[202:205], v170 offset:34816
	ds_read_b128 v[206:209], v170 offset:35840
	ds_read_b128 v[210:213], v170 offset:36864
	ds_read_b128 v[220:223], v170 offset:37888
	ds_read_b128 v[224:227], v170 offset:38912
	ds_read_b128 v[228:231], v170 offset:39936
	global_load_lds_dwordx4 v[236:237], off
	v_lshl_add_u64 v[236:237], s[44:45], 0, v[140:141]
	s_mov_b32 m0, s12
	s_nop 0
	global_load_lds_dwordx4 v[236:237], off
	s_waitcnt vmcnt(8)
	s_waitcnt lgkmcnt(0)
	s_barrier
	s_waitcnt lgkmcnt(0)
	v_mfma_f32_16x16x32_bf16 v[0:3], v[134:137], v[194:197], v[0:3]
	v_mfma_f32_16x16x32_bf16 v[4:7], v[156:159], v[194:197], v[4:7]
	v_mfma_f32_16x16x32_bf16 v[16:19], v[134:137], v[202:205], v[16:19]
	v_mfma_f32_16x16x32_bf16 v[20:23], v[156:159], v[202:205], v[20:23]
	v_mfma_f32_16x16x32_bf16 v[46:49], v[134:137], v[210:213], v[46:49]
	v_mfma_f32_16x16x32_bf16 v[50:53], v[156:159], v[210:213], v[50:53]
	v_mfma_f32_16x16x32_bf16 v[66:69], v[134:137], v[224:227], v[66:69]
	v_mfma_f32_16x16x32_bf16 v[70:73], v[156:159], v[224:227], v[70:73]
	v_mfma_f32_16x16x32_bf16 v[0:3], v[152:155], v[198:201], v[0:3]
	v_mfma_f32_16x16x32_bf16 v[4:7], v[160:163], v[198:201], v[4:7]
	v_mfma_f32_16x16x32_bf16 v[16:19], v[152:155], v[206:209], v[16:19]
	v_mfma_f32_16x16x32_bf16 v[20:23], v[160:163], v[206:209], v[20:23]
	v_mfma_f32_16x16x32_bf16 v[46:49], v[152:155], v[220:223], v[46:49]
	v_mfma_f32_16x16x32_bf16 v[50:53], v[160:163], v[220:223], v[50:53]
	v_mfma_f32_16x16x32_bf16 v[66:69], v[152:155], v[228:231], v[66:69]
	v_mfma_f32_16x16x32_bf16 v[70:73], v[160:163], v[228:231], v[70:73]
	v_mfma_f32_16x16x32_bf16 v[8:11], v[178:181], v[194:197], v[8:11]
	v_mfma_f32_16x16x32_bf16 v[12:15], v[186:189], v[194:197], v[12:15]
	v_mfma_f32_16x16x32_bf16 v[24:27], v[178:181], v[202:205], v[24:27]
	v_mfma_f32_16x16x32_bf16 v[28:31], v[186:189], v[202:205], v[28:31]
	v_mfma_f32_16x16x32_bf16 v[54:57], v[178:181], v[210:213], v[54:57]
	v_mfma_f32_16x16x32_bf16 v[58:61], v[186:189], v[210:213], v[58:61]
	v_mfma_f32_16x16x32_bf16 v[74:77], v[178:181], v[224:227], v[74:77]
	v_mfma_f32_16x16x32_bf16 v[78:81], v[186:189], v[224:227], v[78:81]
	v_mfma_f32_16x16x32_bf16 v[8:11], v[182:185], v[198:201], v[8:11]
	v_mfma_f32_16x16x32_bf16 v[12:15], v[190:193], v[198:201], v[12:15]
	v_mfma_f32_16x16x32_bf16 v[24:27], v[182:185], v[206:209], v[24:27]
	v_mfma_f32_16x16x32_bf16 v[28:31], v[190:193], v[206:209], v[28:31]
	v_mfma_f32_16x16x32_bf16 v[54:57], v[182:185], v[220:223], v[54:57]
	v_mfma_f32_16x16x32_bf16 v[58:61], v[190:193], v[220:223], v[58:61]
	v_mfma_f32_16x16x32_bf16 v[74:77], v[182:185], v[228:231], v[74:77]
	v_mfma_f32_16x16x32_bf16 v[78:81], v[190:193], v[228:231], v[78:81]
	s_barrier
	s_mov_b32 m0, s39
	v_lshl_add_u64 v[164:165], v[164:165], 0, s[28:29]
	s_add_u32 s26, s26, 0x40080
	ds_read_b128 v[194:197], v170 offset:49152
	ds_read_b128 v[198:201], v170 offset:50176
	ds_read_b128 v[202:205], v170 offset:51200
	ds_read_b128 v[206:209], v170 offset:52224
	ds_read_b128 v[210:213], v170 offset:53248
	ds_read_b128 v[220:223], v170 offset:54272
	ds_read_b128 v[224:227], v170 offset:55296
	ds_read_b128 v[228:231], v170 offset:56320
	global_load_lds_dwordx4 v[164:165], off
	v_lshl_add_u64 v[164:165], v[214:215], 0, s[28:29]
	s_mov_b32 m0, s64
	s_addc_u32 s27, s27, 0
	global_load_lds_dwordx4 v[164:165], off
	v_lshl_add_u64 v[164:165], s[26:27], 0, v[32:33]
	s_mov_b32 m0, s65
	s_nop 0
	global_load_lds_dwordx4 v[164:165], off
	v_lshl_add_u64 v[164:165], s[26:27], 0, v[142:143]
	s_mov_b32 m0, s0
	s_nop 0
	global_load_lds_dwordx4 v[164:165], off
	v_lshl_add_u64 v[164:165], v[232:233], 0, s[28:29]
	s_mov_b32 m0, s84
	s_nop 0
	global_load_lds_dwordx4 v[164:165], off
	v_lshl_add_u64 v[164:165], v[234:235], 0, s[28:29]
	s_mov_b32 m0, s85
	s_nop 0
	global_load_lds_dwordx4 v[164:165], off
	s_waitcnt vmcnt(8)
	s_waitcnt lgkmcnt(0)
	s_barrier
	s_waitcnt lgkmcnt(0)
	v_mfma_f32_16x16x32_bf16 v[82:85], v[134:137], v[194:197], v[82:85]
	v_mfma_f32_16x16x32_bf16 v[86:89], v[156:159], v[194:197], v[86:89]
	v_mfma_f32_16x16x32_bf16 v[106:109], v[134:137], v[202:205], v[106:109]
	v_mfma_f32_16x16x32_bf16 v[114:117], v[156:159], v[202:205], v[114:117]
	v_mfma_f32_16x16x32_bf16 v[126:129], v[134:137], v[210:213], v[126:129]
	v_mfma_f32_16x16x32_bf16 v[110:113], v[156:159], v[210:213], v[110:113]
	v_mfma_f32_16x16x32_bf16 v[62:65], v[134:137], v[224:227], v[62:65]
	v_mfma_f32_16x16x32_bf16 v[42:45], v[156:159], v[224:227], v[42:45]
	v_mfma_f32_16x16x32_bf16 v[82:85], v[152:155], v[198:201], v[82:85]
	v_mfma_f32_16x16x32_bf16 v[86:89], v[160:163], v[198:201], v[86:89]
	v_mfma_f32_16x16x32_bf16 v[106:109], v[152:155], v[206:209], v[106:109]
	v_mfma_f32_16x16x32_bf16 v[114:117], v[160:163], v[206:209], v[114:117]
	v_mfma_f32_16x16x32_bf16 v[126:129], v[152:155], v[220:223], v[126:129]
	v_mfma_f32_16x16x32_bf16 v[110:113], v[160:163], v[220:223], v[110:113]
	v_mfma_f32_16x16x32_bf16 v[62:65], v[152:155], v[228:231], v[62:65]
	v_mfma_f32_16x16x32_bf16 v[42:45], v[160:163], v[228:231], v[42:45]
	v_mfma_f32_16x16x32_bf16 v[90:93], v[178:181], v[194:197], v[90:93]
	v_mfma_f32_16x16x32_bf16 v[94:97], v[186:189], v[194:197], v[94:97]
	v_mfma_f32_16x16x32_bf16 v[118:121], v[178:181], v[202:205], v[118:121]
	v_mfma_f32_16x16x32_bf16 v[122:125], v[186:189], v[202:205], v[122:125]
	v_mfma_f32_16x16x32_bf16 v[102:105], v[178:181], v[210:213], v[102:105]
	v_mfma_f32_16x16x32_bf16 v[98:101], v[186:189], v[210:213], v[98:101]
	v_mfma_f32_16x16x32_bf16 v[38:41], v[178:181], v[224:227], v[38:41]
	v_mfma_f32_16x16x32_bf16 v[34:37], v[186:189], v[224:227], v[34:37]
	v_mfma_f32_16x16x32_bf16 v[90:93], v[182:185], v[198:201], v[90:93]
	v_mfma_f32_16x16x32_bf16 v[94:97], v[190:193], v[198:201], v[94:97]
	v_mfma_f32_16x16x32_bf16 v[118:121], v[182:185], v[206:209], v[118:121]
	v_mfma_f32_16x16x32_bf16 v[122:125], v[190:193], v[206:209], v[122:125]
	v_mfma_f32_16x16x32_bf16 v[102:105], v[182:185], v[220:223], v[102:105]
	v_mfma_f32_16x16x32_bf16 v[98:101], v[190:193], v[220:223], v[98:101]
	v_mfma_f32_16x16x32_bf16 v[38:41], v[182:185], v[228:231], v[38:41]
	v_mfma_f32_16x16x32_bf16 v[34:37], v[190:193], v[228:231], v[34:37]
	s_barrier
	s_add_i32 s26, s49, 2
	s_add_u32 s24, s24, 0x100
	s_addc_u32 s25, s25, 0
	v_lshl_add_u64 v[132:133], v[132:133], 0, s[30:31]
	v_lshl_add_u64 v[130:131], v[130:131], 0, s[30:31]
	s_cmp_ge_i32 s49, s87
	s_mov_b32 s49, s26
	s_cbranch_scc0 .LBB0_405
	s_and_b64 vcc, exec, s[56:57]
	s_cbranch_vccz .LBB0_408
	s_barrier

.LBB0_584:
	s_add_u32 s47, s56, 0xfffc0080
	s_addc_u32 s58, s57, -1
	s_add_i32 s65, 0, 0x10000
	s_cmp_eq_u32 s45, 12
	s_cselect_b32 s61, s53, s58
	s_cselect_b32 s60, s52, s47
	s_cselect_b32 s59, s55, s19
	s_cselect_b32 s58, s54, s18
	s_add_i32 s47, 0, 0x14000
	v_add_u32_e32 v152, s65, v157
	v_add_u32_e32 v159, s47, v157
	ds_read_b128 v[130:133], v152
	ds_read_b128 v[144:147], v152 offset:1024
	ds_read_b128 v[148:151], v152 offset:2048
	ds_read_b128 v[152:155], v152 offset:3072
	ds_read_b128 v[176:179], v159
	ds_read_b128 v[180:183], v159 offset:1024
	ds_read_b128 v[184:187], v159 offset:2048
	ds_read_b128 v[188:191], v159 offset:3072
	v_lshl_add_u64 v[160:161], s[56:57], 0, v[140:141]
	s_add_i32 m0, s1, 0xc000
	ds_read_b128 v[192:195], v158
	ds_read_b128 v[196:199], v158 offset:1024
	ds_read_b128 v[200:203], v158 offset:2048
	ds_read_b128 v[204:207], v158 offset:3072
	ds_read_b128 v[208:211], v158 offset:4096
	ds_read_b128 v[212:215], v158 offset:5120
	ds_read_b128 v[224:227], v158 offset:6144
	ds_read_b128 v[228:231], v158 offset:7168
	global_load_lds_dwordx4 v[160:161], off
	v_lshl_add_u64 v[160:161], s[56:57], 0, v[142:143]
	s_add_i32 m0, s1, 0xe000
	s_nop 0
	global_load_lds_dwordx4 v[160:161], off
	s_waitcnt vmcnt(8)
	s_waitcnt lgkmcnt(0)
	s_barrier
	s_waitcnt lgkmcnt(0)
	v_mfma_f32_16x16x32_bf16 v[126:129], v[130:133], v[192:195], v[126:129]
	v_mfma_f32_16x16x32_bf16 v[122:125], v[148:151], v[192:195], v[122:125]
	v_mfma_f32_16x16x32_bf16 v[118:121], v[130:133], v[200:203], v[118:121]
	v_mfma_f32_16x16x32_bf16 v[110:113], v[148:151], v[200:203], v[110:113]
	v_mfma_f32_16x16x32_bf16 v[102:105], v[130:133], v[208:211], v[102:105]
	v_mfma_f32_16x16x32_bf16 v[94:97], v[148:151], v[208:211], v[94:97]
	v_mfma_f32_16x16x32_bf16 v[86:89], v[130:133], v[224:227], v[86:89]
	v_mfma_f32_16x16x32_bf16 v[78:81], v[148:151], v[224:227], v[78:81]
	v_mfma_f32_16x16x32_bf16 v[126:129], v[144:147], v[196:199], v[126:129]
	v_mfma_f32_16x16x32_bf16 v[122:125], v[152:155], v[196:199], v[122:125]
	v_mfma_f32_16x16x32_bf16 v[118:121], v[144:147], v[204:207], v[118:121]
	v_mfma_f32_16x16x32_bf16 v[110:113], v[152:155], v[204:207], v[110:113]
	v_mfma_f32_16x16x32_bf16 v[102:105], v[144:147], v[212:215], v[102:105]
	v_mfma_f32_16x16x32_bf16 v[94:97], v[152:155], v[212:215], v[94:97]
	v_mfma_f32_16x16x32_bf16 v[86:89], v[144:147], v[228:231], v[86:89]
	v_mfma_f32_16x16x32_bf16 v[78:81], v[152:155], v[228:231], v[78:81]
	v_mfma_f32_16x16x32_bf16 v[114:117], v[176:179], v[192:195], v[114:117]
	v_mfma_f32_16x16x32_bf16 v[106:109], v[184:187], v[192:195], v[106:109]
	v_mfma_f32_16x16x32_bf16 v[98:101], v[176:179], v[200:203], v[98:101]
	v_mfma_f32_16x16x32_bf16 v[90:93], v[184:187], v[200:203], v[90:93]
	v_mfma_f32_16x16x32_bf16 v[82:85], v[176:179], v[208:211], v[82:85]
	v_mfma_f32_16x16x32_bf16 v[74:77], v[184:187], v[208:211], v[74:77]
	v_mfma_f32_16x16x32_bf16 v[70:73], v[176:179], v[224:227], v[70:73]
	v_mfma_f32_16x16x32_bf16 v[66:69], v[184:187], v[224:227], v[66:69]
	v_mfma_f32_16x16x32_bf16 v[114:117], v[180:183], v[196:199], v[114:117]
	v_mfma_f32_16x16x32_bf16 v[106:109], v[188:191], v[196:199], v[106:109]
	v_mfma_f32_16x16x32_bf16 v[98:101], v[180:183], v[204:207], v[98:101]
	v_mfma_f32_16x16x32_bf16 v[90:93], v[188:191], v[204:207], v[90:93]
	v_mfma_f32_16x16x32_bf16 v[82:85], v[180:183], v[212:215], v[82:85]
	v_mfma_f32_16x16x32_bf16 v[74:77], v[188:191], v[212:215], v[74:77]
	v_mfma_f32_16x16x32_bf16 v[70:73], v[180:183], v[228:231], v[70:73]
	v_mfma_f32_16x16x32_bf16 v[66:69], v[188:191], v[228:231], v[66:69]
	s_barrier
	s_add_i32 s65, s65, s0
	v_lshl_add_u64 v[160:161], s[58:59], 0, v[32:33]
	s_mov_b32 m0, s65
	ds_read_b128 v[192:195], v158 offset:16384
	ds_read_b128 v[196:199], v158 offset:17408
	ds_read_b128 v[200:203], v158 offset:18432
	ds_read_b128 v[204:207], v158 offset:19456
	ds_read_b128 v[208:211], v158 offset:20480
	ds_read_b128 v[212:215], v158 offset:21504
	ds_read_b128 v[224:227], v158 offset:22528
	ds_read_b128 v[228:231], v158 offset:23552
	global_load_lds_dwordx4 v[160:161], off
	s_add_i32 m0, s65, 0x2000
	s_add_u32 s66, s58, 0x40000
	v_lshl_add_u64 v[162:163], s[58:59], 0, v[134:135]
	s_addc_u32 s67, s59, 0
	s_add_i32 s47, s47, s0
	global_load_lds_dwordx4 v[162:163], off
	v_lshl_add_u64 v[164:165], s[66:67], 0, v[32:33]
	s_mov_b32 m0, s47
	v_lshl_add_u64 v[220:221], s[60:61], 0, v[136:137]
	global_load_lds_dwordx4 v[164:165], off
	v_lshl_add_u64 v[164:165], s[66:67], 0, v[134:135]
	s_add_i32 m0, s47, 0x2000
	s_nop 0
	global_load_lds_dwordx4 v[164:165], off
	v_lshl_add_u64 v[164:165], s[60:61], 0, v[138:139]
	s_mov_b32 m0, s1
	s_nop 0
	global_load_lds_dwordx4 v[164:165], off
	s_mov_b32 m0, s4
	s_nop 0
	global_load_lds_dwordx4 v[220:221], off
	s_waitcnt vmcnt(8)
	s_waitcnt lgkmcnt(0)
	s_barrier
	s_waitcnt lgkmcnt(0)
	v_mfma_f32_16x16x32_bf16 v[62:65], v[130:133], v[192:195], v[62:65]
	v_mfma_f32_16x16x32_bf16 v[58:61], v[148:151], v[192:195], v[58:61]
	v_mfma_f32_16x16x32_bf16 v[54:57], v[130:133], v[200:203], v[54:57]
	v_mfma_f32_16x16x32_bf16 v[46:49], v[148:151], v[200:203], v[46:49]
	v_mfma_f32_16x16x32_bf16 v[38:41], v[130:133], v[208:211], v[38:41]
	v_mfma_f32_16x16x32_bf16 v[28:31], v[148:151], v[208:211], v[28:31]
	v_mfma_f32_16x16x32_bf16 v[20:23], v[130:133], v[224:227], v[20:23]
	v_mfma_f32_16x16x32_bf16 v[12:15], v[148:151], v[224:227], v[12:15]
	v_mfma_f32_16x16x32_bf16 v[62:65], v[144:147], v[196:199], v[62:65]
	v_mfma_f32_16x16x32_bf16 v[58:61], v[152:155], v[196:199], v[58:61]
	v_mfma_f32_16x16x32_bf16 v[54:57], v[144:147], v[204:207], v[54:57]
	v_mfma_f32_16x16x32_bf16 v[46:49], v[152:155], v[204:207], v[46:49]
	v_mfma_f32_16x16x32_bf16 v[38:41], v[144:147], v[212:215], v[38:41]
	v_mfma_f32_16x16x32_bf16 v[28:31], v[152:155], v[212:215], v[28:31]
	v_mfma_f32_16x16x32_bf16 v[20:23], v[144:147], v[228:231], v[20:23]
	v_mfma_f32_16x16x32_bf16 v[12:15], v[152:155], v[228:231], v[12:15]
	v_mfma_f32_16x16x32_bf16 v[50:53], v[176:179], v[192:195], v[50:53]
	v_mfma_f32_16x16x32_bf16 v[42:45], v[184:187], v[192:195], v[42:45]
	v_mfma_f32_16x16x32_bf16 v[34:37], v[176:179], v[200:203], v[34:37]
	v_mfma_f32_16x16x32_bf16 v[24:27], v[184:187], v[200:203], v[24:27]
	v_mfma_f32_16x16x32_bf16 v[16:19], v[176:179], v[208:211], v[16:19]
	v_mfma_f32_16x16x32_bf16 v[8:11], v[184:187], v[208:211], v[8:11]
	v_mfma_f32_16x16x32_bf16 v[4:7], v[176:179], v[224:227], v[4:7]
	v_mfma_f32_16x16x32_bf16 v[0:3], v[184:187], v[224:227], v[0:3]
	v_mfma_f32_16x16x32_bf16 v[50:53], v[180:183], v[196:199], v[50:53]
	v_mfma_f32_16x16x32_bf16 v[42:45], v[188:191], v[196:199], v[42:45]
	v_mfma_f32_16x16x32_bf16 v[34:37], v[180:183], v[204:207], v[34:37]
	v_mfma_f32_16x16x32_bf16 v[24:27], v[188:191], v[204:207], v[24:27]
	v_mfma_f32_16x16x32_bf16 v[16:19], v[180:183], v[212:215], v[16:19]
	v_mfma_f32_16x16x32_bf16 v[8:11], v[188:191], v[212:215], v[8:11]
	v_mfma_f32_16x16x32_bf16 v[4:7], v[180:183], v[228:231], v[4:7]
	v_mfma_f32_16x16x32_bf16 v[0:3], v[188:191], v[228:231], v[0:3]
	s_barrier
	s_add_i32 s47, 0, 0x18000
	s_add_i32 s65, 0, 0x1c000
	v_add_u32_e32 v152, s47, v157
	v_add_u32_e32 v159, s65, v157
	ds_read_b128 v[130:133], v152
	ds_read_b128 v[144:147], v152 offset:1024
	ds_read_b128 v[148:151], v152 offset:2048
	ds_read_b128 v[152:155], v152 offset:3072
	ds_read_b128 v[176:179], v159
	ds_read_b128 v[180:183], v159 offset:1024
	ds_read_b128 v[184:187], v159 offset:2048
	ds_read_b128 v[188:191], v159 offset:3072
	s_add_u32 s60, s60, 0x40000
	s_addc_u32 s61, s61, 0
	s_mov_b32 m0, s5
	v_lshl_add_u64 v[222:223], s[60:61], 0, v[138:139]
	ds_read_b128 v[192:195], v158 offset:32768
	ds_read_b128 v[196:199], v158 offset:33792
	ds_read_b128 v[200:203], v158 offset:34816
	ds_read_b128 v[204:207], v158 offset:35840
	ds_read_b128 v[208:211], v158 offset:36864
	ds_read_b128 v[212:215], v158 offset:37888
	ds_read_b128 v[224:227], v158 offset:38912
	ds_read_b128 v[228:231], v158 offset:39936
	global_load_lds_dwordx4 v[222:223], off
	v_lshl_add_u64 v[222:223], s[60:61], 0, v[136:137]
	s_mov_b32 m0, s8
	s_nop 0
	global_load_lds_dwordx4 v[222:223], off
	s_waitcnt vmcnt(8)
	s_waitcnt lgkmcnt(0)
	s_barrier
	s_waitcnt lgkmcnt(0)
	v_mfma_f32_16x16x32_bf16 v[126:129], v[130:133], v[192:195], v[126:129]
	v_mfma_f32_16x16x32_bf16 v[122:125], v[148:151], v[192:195], v[122:125]
	v_mfma_f32_16x16x32_bf16 v[118:121], v[130:133], v[200:203], v[118:121]
	v_mfma_f32_16x16x32_bf16 v[110:113], v[148:151], v[200:203], v[110:113]
	v_mfma_f32_16x16x32_bf16 v[102:105], v[130:133], v[208:211], v[102:105]
	v_mfma_f32_16x16x32_bf16 v[94:97], v[148:151], v[208:211], v[94:97]
	v_mfma_f32_16x16x32_bf16 v[86:89], v[130:133], v[224:227], v[86:89]
	v_mfma_f32_16x16x32_bf16 v[78:81], v[148:151], v[224:227], v[78:81]
	v_mfma_f32_16x16x32_bf16 v[126:129], v[144:147], v[196:199], v[126:129]
	v_mfma_f32_16x16x32_bf16 v[122:125], v[152:155], v[196:199], v[122:125]
	v_mfma_f32_16x16x32_bf16 v[118:121], v[144:147], v[204:207], v[118:121]
	v_mfma_f32_16x16x32_bf16 v[110:113], v[152:155], v[204:207], v[110:113]
	v_mfma_f32_16x16x32_bf16 v[102:105], v[144:147], v[212:215], v[102:105]
	v_mfma_f32_16x16x32_bf16 v[94:97], v[152:155], v[212:215], v[94:97]
	v_mfma_f32_16x16x32_bf16 v[86:89], v[144:147], v[228:231], v[86:89]
	v_mfma_f32_16x16x32_bf16 v[78:81], v[152:155], v[228:231], v[78:81]
	v_mfma_f32_16x16x32_bf16 v[114:117], v[176:179], v[192:195], v[114:117]
	v_mfma_f32_16x16x32_bf16 v[106:109], v[184:187], v[192:195], v[106:109]
	v_mfma_f32_16x16x32_bf16 v[98:101], v[176:179], v[200:203], v[98:101]
	v_mfma_f32_16x16x32_bf16 v[90:93], v[184:187], v[200:203], v[90:93]
	v_mfma_f32_16x16x32_bf16 v[82:85], v[176:179], v[208:211], v[82:85]
	v_mfma_f32_16x16x32_bf16 v[74:77], v[184:187], v[208:211], v[74:77]
	v_mfma_f32_16x16x32_bf16 v[70:73], v[176:179], v[224:227], v[70:73]
	v_mfma_f32_16x16x32_bf16 v[66:69], v[184:187], v[224:227], v[66:69]
	v_mfma_f32_16x16x32_bf16 v[114:117], v[180:183], v[196:199], v[114:117]
	v_mfma_f32_16x16x32_bf16 v[106:109], v[188:191], v[196:199], v[106:109]
	v_mfma_f32_16x16x32_bf16 v[98:101], v[180:183], v[204:207], v[98:101]
	v_mfma_f32_16x16x32_bf16 v[90:93], v[188:191], v[204:207], v[90:93]
	v_mfma_f32_16x16x32_bf16 v[82:85], v[180:183], v[212:215], v[82:85]
	v_mfma_f32_16x16x32_bf16 v[74:77], v[188:191], v[212:215], v[74:77]
	v_mfma_f32_16x16x32_bf16 v[70:73], v[180:183], v[228:231], v[70:73]
	v_mfma_f32_16x16x32_bf16 v[66:69], v[188:191], v[228:231], v[66:69]
	s_barrier
	s_add_i32 s47, s47, s0
	v_lshl_add_u64 v[160:161], v[160:161], 0, s[28:29]
	s_mov_b32 m0, s47
	ds_read_b128 v[192:195], v158 offset:49152
	ds_read_b128 v[196:199], v158 offset:50176
	ds_read_b128 v[200:203], v158 offset:51200
	ds_read_b128 v[204:207], v158 offset:52224
	ds_read_b128 v[208:211], v158 offset:53248
	ds_read_b128 v[212:215], v158 offset:54272
	ds_read_b128 v[224:227], v158 offset:55296
	ds_read_b128 v[228:231], v158 offset:56320
	global_load_lds_dwordx4 v[160:161], off
	s_add_i32 m0, s47, 0x2000
	s_add_u32 s58, s58, 0x40080
	v_lshl_add_u64 v[160:161], v[162:163], 0, s[28:29]
	s_addc_u32 s59, s59, 0
	s_add_i32 s47, s65, s0
	global_load_lds_dwordx4 v[160:161], off
	v_lshl_add_u64 v[160:161], s[58:59], 0, v[32:33]
	s_mov_b32 m0, s47
	s_nop 0
	global_load_lds_dwordx4 v[160:161], off
	v_lshl_add_u64 v[160:161], s[58:59], 0, v[134:135]
	s_add_i32 m0, s47, 0x2000
	s_nop 0
	global_load_lds_dwordx4 v[160:161], off
	v_lshl_add_u64 v[160:161], v[164:165], 0, s[28:29]
	s_mov_b32 m0, s33
	s_nop 0
	global_load_lds_dwordx4 v[160:161], off
	v_lshl_add_u64 v[160:161], v[220:221], 0, s[28:29]
	s_mov_b32 m0, s38
	s_nop 0
	global_load_lds_dwordx4 v[160:161], off
	s_waitcnt vmcnt(8)
	s_waitcnt lgkmcnt(0)
	s_barrier
	s_waitcnt lgkmcnt(0)
	v_mfma_f32_16x16x32_bf16 v[62:65], v[130:133], v[192:195], v[62:65]
	v_mfma_f32_16x16x32_bf16 v[58:61], v[148:151], v[192:195], v[58:61]
	v_mfma_f32_16x16x32_bf16 v[54:57], v[130:133], v[200:203], v[54:57]
	v_mfma_f32_16x16x32_bf16 v[46:49], v[148:151], v[200:203], v[46:49]
	v_mfma_f32_16x16x32_bf16 v[38:41], v[130:133], v[208:211], v[38:41]
	v_mfma_f32_16x16x32_bf16 v[28:31], v[148:151], v[208:211], v[28:31]
	v_mfma_f32_16x16x32_bf16 v[20:23], v[130:133], v[224:227], v[20:23]
	v_mfma_f32_16x16x32_bf16 v[12:15], v[148:151], v[224:227], v[12:15]
	v_mfma_f32_16x16x32_bf16 v[62:65], v[144:147], v[196:199], v[62:65]
	v_mfma_f32_16x16x32_bf16 v[58:61], v[152:155], v[196:199], v[58:61]
	v_mfma_f32_16x16x32_bf16 v[54:57], v[144:147], v[204:207], v[54:57]
	v_mfma_f32_16x16x32_bf16 v[46:49], v[152:155], v[204:207], v[46:49]
	v_mfma_f32_16x16x32_bf16 v[38:41], v[144:147], v[212:215], v[38:41]
	v_mfma_f32_16x16x32_bf16 v[28:31], v[152:155], v[212:215], v[28:31]
	v_mfma_f32_16x16x32_bf16 v[20:23], v[144:147], v[228:231], v[20:23]
	v_mfma_f32_16x16x32_bf16 v[12:15], v[152:155], v[228:231], v[12:15]
	v_mfma_f32_16x16x32_bf16 v[50:53], v[176:179], v[192:195], v[50:53]
	v_mfma_f32_16x16x32_bf16 v[42:45], v[184:187], v[192:195], v[42:45]
	v_mfma_f32_16x16x32_bf16 v[34:37], v[176:179], v[200:203], v[34:37]
	v_mfma_f32_16x16x32_bf16 v[24:27], v[184:187], v[200:203], v[24:27]
	v_mfma_f32_16x16x32_bf16 v[16:19], v[176:179], v[208:211], v[16:19]
	v_mfma_f32_16x16x32_bf16 v[8:11], v[184:187], v[208:211], v[8:11]
	v_mfma_f32_16x16x32_bf16 v[4:7], v[176:179], v[224:227], v[4:7]
	v_mfma_f32_16x16x32_bf16 v[0:3], v[184:187], v[224:227], v[0:3]
	v_mfma_f32_16x16x32_bf16 v[50:53], v[180:183], v[196:199], v[50:53]
	v_mfma_f32_16x16x32_bf16 v[42:45], v[188:191], v[196:199], v[42:45]
	v_mfma_f32_16x16x32_bf16 v[34:37], v[180:183], v[204:207], v[34:37]
	v_mfma_f32_16x16x32_bf16 v[24:27], v[188:191], v[204:207], v[24:27]
	v_mfma_f32_16x16x32_bf16 v[16:19], v[180:183], v[212:215], v[16:19]
	v_mfma_f32_16x16x32_bf16 v[8:11], v[188:191], v[212:215], v[8:11]
	v_mfma_f32_16x16x32_bf16 v[4:7], v[180:183], v[228:231], v[4:7]
	v_mfma_f32_16x16x32_bf16 v[0:3], v[188:191], v[228:231], v[0:3]
	s_barrier
	s_add_i32 s45, s45, 2
	s_add_u32 s56, s56, 0x100
	s_addc_u32 s57, s57, 0
	s_add_u32 s18, s18, 0x100
	s_addc_u32 s19, s19, 0
	s_cmp_gt_u32 s45, 13
	s_cbranch_scc0 .LBB0_584
	s_and_b64 vcc, exec, s[24:25]
	s_cbranch_vccz .LBB0_587
	s_barrier
